# speedup vs baseline: 1.0273x; 1.0081x over previous
; DEVI void attn_item(const Params& p, const int l, const int bh, const int qblk, const float lam, const float osc, char* smem) {
;   const int tid = threadIdx.x, wid = tid >> 6, lane = tid & 63, l31 = lane & 31, hi = lane >> 5;
;   const int b = bh / 6, h = bh % 6;
;   const int qg = wid >> 1, m = wid & 1;
;   const int nkt = 2 * qblk + 2;
;   const int my_last = 2 * qblk + (qg >> 1);
;   const u16* PBC = (const u16*)(p.ws + OFF_PBC);
;   const u16* VT = (const u16*)(p.ws + OFF_VT) + (size_t)(b * 6 + h) * 256 * 8192;
;   const u16* KT = (const u16*)(p.ws + OFF_KT) + (size_t)(b * 6 + h) * 256 * 8192;
;   const size_t tok0 = (size_t)b * SEQ_;
;   float* wsc = (float*)smem + wid * 64;
;   char* stg = smem + 2048;
;   float* obuf = (float*)(smem + 2048);
;   constexpr float C = 0.125f * 1.4426950408889634f;
;   bf16x8 qf[4];
;   {
;     const u16* qp = PBC + (tok0 + (size_t)qblk * 128 + qg * 32 + l31) * 1280 + 512 + h * 128 + m * 64 + hi * 8;
; #pragma unroll
;     for (int d0 = 0; d0 < 4; ++d0) qf[d0] = *(const bf16x8*)(qp + d0 * 16);
;   }
;   const int kkey = tid >> 4, kch = tid & 15;
;   const u16* kg = KT + kkey * 128 + kch * 8;
;   const int klds = (kch >> 3) * 8192 + swz(kkey, kch & 7);
;   const int ve = tid >> 3, vj = tid & 7;
;   const u16* vg = VT + ve * 64 + vj * 8;
;   const int vx = (ve >> 1) & 7;
;   const int vlds0 = 16384 + ve * 128 + ((((vj >> 1) * 2 + 0) ^ vx) << 4) + (vj & 1) * 8;
;   const int vlds1 = 16384 + ve * 128 + ((((vj >> 1) * 2 + 1) ^ vx) << 4) + (vj & 1) * 8;
;     ...
;   float d1 = 0.f, d2 = 0.f;
;   for (int i = 0; i < 64; ++i) { d1 += p.in[25][l * 64 + i] * p.in[26][l * 64 + i]; d2 += p.in[27][l * 64 + i] * p.in[28][l * 64 + i]; }
;   const float lam_init = 0.8f - 0.6f * expf(-0.3f * (float)l);
;   const float lam = expf(d1) - expf(d2) + lam_init;
;   const float osc = 1.f - lam_init;
.LBB0_527:
	s_add_u32 s2, s14, s0
	s_addc_u32 s3, s15, s1
	global_load_dwordx4 v[4:7], v1, s[2:3]
	global_load_dwordx4 v[8:11], v1, s[2:3] offset:16
	s_add_u32 s2, s16, s0
	s_addc_u32 s3, s17, s1
	global_load_dwordx4 v[12:15], v1, s[2:3]
	global_load_dwordx4 v[16:19], v1, s[2:3] offset:16
	s_add_u32 s2, s18, s0
	s_addc_u32 s3, s19, s1
	global_load_dwordx4 v[20:23], v1, s[2:3]
	global_load_dwordx4 v[24:27], v1, s[2:3] offset:16
	s_add_u32 s2, s20, s0
	s_addc_u32 s3, s21, s1
	global_load_dwordx4 v[28:31], v1, s[2:3]
	global_load_dwordx4 v[32:35], v1, s[2:3] offset:16
	s_add_u32 s0, s0, 32
	s_addc_u32 s1, s1, 0
	s_cmpk_eq_i32 s0, 0x100
	s_waitcnt vmcnt(7)
	v_mov_b32_e32 v36, v4
	v_mov_b32_e32 v4, v6
	s_waitcnt vmcnt(6)
	v_mov_b32_e32 v6, v8
	v_mov_b32_e32 v8, v10
	s_waitcnt vmcnt(5)
	v_mov_b32_e32 v10, v12
	v_mov_b32_e32 v12, v14
	s_waitcnt vmcnt(3)
	v_mov_b32_e32 v37, v20
	v_mov_b32_e32 v20, v5
	v_mov_b32_e32 v5, v22
	v_mov_b32_e32 v22, v7
	s_waitcnt vmcnt(2)
	v_mov_b32_e32 v7, v24
	v_mov_b32_e32 v24, v9
	v_mov_b32_e32 v9, v26
	v_mov_b32_e32 v26, v11
	s_waitcnt vmcnt(1)
	v_mov_b32_e32 v11, v28
	v_mov_b32_e32 v28, v13
	v_pk_fma_f32 v[2:3], v[36:37], v[10:11], v[2:3]
	v_mov_b32_e32 v13, v30
	v_pk_fma_f32 v[2:3], v[20:21], v[28:29], v[2:3]
	v_mov_b32_e32 v30, v15
	v_pk_fma_f32 v[2:3], v[4:5], v[12:13], v[2:3]
	v_mov_b32_e32 v14, v16
	s_waitcnt vmcnt(0)
	v_mov_b32_e32 v15, v32
	v_pk_fma_f32 v[2:3], v[22:23], v[30:31], v[2:3]
	v_mov_b32_e32 v32, v17
	v_pk_fma_f32 v[2:3], v[6:7], v[14:15], v[2:3]
	v_mov_b32_e32 v16, v18
	v_mov_b32_e32 v17, v34
	v_pk_fma_f32 v[2:3], v[24:25], v[32:33], v[2:3]
	v_mov_b32_e32 v34, v19
	v_pk_fma_f32 v[2:3], v[8:9], v[16:17], v[2:3]
	s_nop 0
	v_pk_fma_f32 v[2:3], v[26:27], v[34:35], v[2:3]
	s_cbranch_scc0 .LBB0_527
	v_mul_f32_e32 v1, 0x3fb8aa3b, v2
	s_mov_b32 s0, 0x3fb8aa3b
	v_rndne_f32_e32 v4, v1
	v_sub_f32_e32 v5, v1, v4
	v_fma_f32 v1, v2, s0, -v1
	v_fmac_f32_e32 v1, 0x32a5705f, v2
	v_add_f32_e32 v1, v5, v1
	v_exp_f32_e32 v1, v1
	v_cvt_i32_f32_e32 v4, v4
	s_mov_b32 s1, 0xc2ce8ed0
	v_cmp_ngt_f32_e32 vcc, s1, v2
	s_mov_b32 s2, 0x42b17218
	v_ldexp_f32 v1, v1, v4
	v_mul_f32_e32 v4, 0x3fb8aa3b, v3
	v_rndne_f32_e32 v5, v4
	v_sub_f32_e32 v6, v4, v5
	v_fma_f32 v4, v3, s0, -v4
	v_fmac_f32_e32 v4, 0x32a5705f, v3
	v_add_f32_e32 v4, v6, v4
	v_exp_f32_e32 v4, v4
	v_cvt_i32_f32_e32 v5, v5
	v_cndmask_b32_e32 v1, 0, v1, vcc
	v_mov_b32_e32 v6, 0x7f800000
	v_cmp_nlt_f32_e32 vcc, s2, v2
	v_ldexp_f32 v2, v4, v5
	v_bfe_u32 v9, v0, 4, 6
	v_cndmask_b32_e32 v1, v6, v1, vcc
	v_cmp_ngt_f32_e32 vcc, s1, v3
	v_lshlrev_b32_e32 v10, 7, v9
	v_and_b32_e32 v14, 6, v0
	v_cndmask_b32_e32 v2, 0, v2, vcc
	v_cmp_nlt_f32_e32 vcc, s2, v3
	s_movk_i32 s2, 0x3ff
	v_bfe_u32 v3, v0, 5, 5
	v_cndmask_b32_e32 v2, v6, v2, vcc
	v_sub_f32_e32 v1, v1, v2
	v_bitop3_b32 v6, v3, v0, s2 bitop3:0x78
	v_add_f32_e32 v196, 0x3e4ccccc, v1
	v_and_b32_e32 v1, 0x3ff, v0
	v_lshlrev_b32_e32 v6, 4, v6
	v_lshl_or_b32 v12, v1, 10, v6
	s_movk_i32 s2, 0x2070
	v_and_or_b32 v17, v12, s2, v10
	v_bfe_u32 v10, v0, 1, 3
	v_bfe_u32 v195, v1, 5, 1
	v_bitop3_b32 v3, v3, v10, 1 bitop3:0x6c
	v_lshlrev_b32_e32 v202, 4, v3
	v_bitop3_b32 v3, v195, v10, 2 bitop3:0x36
	v_lshlrev_b32_e32 v203, 4, v3
	v_bitop3_b32 v3, v195, v10, 4 bitop3:0x36
	v_and_b32_e32 v166, 31, v0
	v_bfe_u32 v168, v0, 2, 8
	v_lshlrev_b32_e32 v11, 3, v1
	v_lshlrev_b32_e32 v16, 4, v1
	v_bitop3_b32 v15, v9, v14, 7 bitop3:0x6c
	v_lshlrev_b32_e32 v204, 4, v3
	v_bitop3_b32 v3, v195, v10, 6 bitop3:0x36
	v_and_b32_e32 v8, 0x60, v168
	v_mov_b32_e32 v173, 0
	v_bfe_u32 v13, v1, 4, 3
	v_and_b32_e32 v6, 0x1f80, v16
	v_lshlrev_b32_e32 v15, 4, v15
	v_and_b32_e32 v198, 8, v11
	v_lshlrev_b32_e32 v205, 4, v3
	v_lshlrev_b32_e32 v199, 2, v166
	v_and_b32_e32 v3, 64, v1
	v_lshlrev_b32_e32 v172, 8, v9
	v_bfe_u32 v5, v1, 6, 1
	v_and_b32_e32 v7, 0x1c0, v0
	v_bitop3_b32 v11, v14, v13, 1 bitop3:0x36
	v_or3_b32 v18, v15, v6, v198
	v_lshl_add_u32 v200, v166, 7, 16
	v_cmp_ne_u32_e64 s[6:7], 0, v3
	v_lshl_or_b32 v3, v195, 2, v8
	v_add_u32_e32 v171, 16, v199
	s_movk_i32 s8, 0x240
	v_lshl_add_u64 v[12:13], s[28:29], 0, v[172:173]
	v_and_b32_e32 v14, 0xf0, v16
	v_mov_b32_e32 v15, v173
	v_lshlrev_b32_e32 v2, 6, v5
	v_lshl_add_u32 v201, v5, 13, v200
	v_lshl_add_u32 v206, v7, 2, 16
	v_cmp_eq_u32_e64 s[4:5], 0, v5
	v_mad_u32_u24 v208, v3, s8, v171
	v_and_b32_e32 v3, 3, v0
	v_mad_u32_u24 v5, v168, s8, 16
	v_lshl_add_u64 v[12:13], v[12:13], 0, v[14:15]
	s_mov_b64 s[8:9], 0x22a00000
	v_mov_b32_e32 v7, v173
	v_or_b32_e32 v170, v8, v166
	v_lshlrev_b32_e32 v11, 4, v11
	v_lshlrev_b32_e32 v8, 4, v3
	v_lshlrev_b32_e32 v10, 2, v3
	v_lshl_add_u64 v[174:175], v[12:13], 0, s[8:9]
	v_lshl_add_u64 v[12:13], s[28:29], 0, v[6:7]
	v_and_b32_e32 v14, 0x70, v16
	v_and_b32_e32 v3, 15, v0
	s_add_u32 s10, s28, 0x3dd80000
	v_lshlrev_b32_e32 v4, 3, v195
	v_or3_b32 v11, v11, v6, v198
	v_lshl_add_u64 v[12:13], v[12:13], 0, v[14:15]
	s_mov_b64 s[8:9], 0x25a00000
	v_mov_b32_e32 v9, v173
	v_lshl_or_b32 v180, v3, 4, v172
	v_and_b32_e32 v3, 7, v0
	v_lshlrev_b32_e32 v184, 1, v2
	v_mbcnt_lo_u32_b32 v2, -1, 0
	s_mov_b32 s73, 0
	s_addc_u32 s34, s29, 0
	v_cmp_eq_u32_e64 s[0:1], 0, v1
	v_bfe_u32 v167, v0, 6, 4
	v_bfe_u32 v197, v0, 8, 2
	v_cmp_eq_u32_e64 s[2:3], 0, v195
	v_add_u32_e32 v207, v206, v199
	v_lshlrev_b32_e32 v194, 4, v195
	v_mov_b32_e32 v169, v173
	v_lshl_add_u64 v[176:177], v[12:13], 0, s[8:9]
	v_lshl_add_u64 v[178:179], s[22:23], 0, v[8:9]
	v_mov_b32_e32 v181, v173
	v_lshl_or_b32 v182, v3, 4, v6
	v_mov_b32_e32 v183, v173
	v_lshlrev_b32_e32 v186, 1, v4
	s_movk_i32 s35, 0x2000
	s_mov_b32 s36, 0x42800000
	s_mov_b32 s78, 0x3e38aa3b
	v_add_u32_e32 v209, v5, v8
	v_mov_b32_e32 v210, 0x3727c5ac
	v_lshlrev_b32_e32 v172, 1, v10
	v_mov_b32_e32 v211, 0xa00
	v_add_u32_e32 v212, 16, v17
	v_add_u32_e32 v213, 16, v18
	v_add_u32_e32 v214, 16, v11
	v_mbcnt_hi_u32_b32 v193, -1, v2
	s_mov_b32 s37, 0
	v_lshrrev_b32_e32 v180, 3, v0
	v_bfe_u32 v181, v0, 4, 3
	v_and_b32_e32 v188, 7, v0
	v_xor_b32_e32 v181, v188, v181
	v_lshlrev_b32_e32 v180, 8, v180
	v_lshl_or_b32 v180, v181, 4, v180
	v_mov_b32_e32 v181, 0
	v_readfirstlane_b32 s101, v0
	s_lshr_b32 s101, s101, 6
	s_lshl_b32 s101, s101, 10
	v_lshrrev_b32_e32 v253, 3, v0
	v_bfe_u32 v190, v0, 4, 3
	v_and_b32_e32 v191, 7, v0
	v_xor_b32_e32 v190, v191, v190
	v_lshlrev_b32_e32 v253, 7, v253
	v_lshl_or_b32 v182, v190, 4, v253
	v_mov_b32_e32 v183, 0
	v_add_u32_e32 v253, 16, v182
	v_add_u32_e32 v242, 0x4000, v180
	v_add_u32_e32 v243, 0x2ffc000, v182
	v_add_u32_e32 v244, 0x2ffe000, v182
	v_add_u32_e32 v245, 0x3000000, v182
	v_add_u32_e32 v246, 0x3002000, v182
	s_branch .LBB0_530

; #define K_LOAD(kt) do { sk0 = *(const bf16x8*)(kg + (size_t)(kt) * 8192); sk1 = *(const bf16x8*)(kg + (size_t)(kt) * 8192 + 4096); } while (0)
; #define V_LOAD(kt) do { sv0 = *(const bf16x8*)(vg + (size_t)(kt) * 8192); sv1 = *(const bf16x8*)(vg + (size_t)(kt) * 8192 + 4096); } while (0)
; #define K_STORE(bi) do { char* s_ = kbuf + (bi) * 16384; *(bf16x8*)(s_ + klds) = sk0; *(bf16x8*)(s_ + klds + 4096) = sk1; } while (0)
; DEVI void attn_item(const Params& p, const int l, const int bh, const int qblk, const float lam, const float osc, char* smem) {
;     ...
;   bf16x8 qf[4];
;   {
;     const u16* qp = PBC + (tok0 + (size_t)qblk * 128 + qg * 32 + l31) * 1280 + 512 + h * 128 + m * 64 + hi * 8;
; #pragma unroll
;     for (int d0 = 0; d0 < 4; ++d0) qf[d0] = *(const bf16x8*)(qp + d0 * 16);
;   }
;   const int kkey = tid >> 4, kch = tid & 15;
;   const u16* kg = KT + kkey * 128 + kch * 8;
;   const int klds = (kch >> 3) * 8192 + swz(kkey, kch & 7);
;   const int ve = tid >> 3, vj = tid & 7;
;   const u16* vg = VT + ve * 64 + vj * 8;
;   const int vx = (ve >> 1) & 7;
;   const int vlds0 = 16384 + ve * 128 + ((((vj >> 1) * 2 + 0) ^ vx) << 4) + (vj & 1) * 8;
;   const int vlds1 = 16384 + ve * 128 + ((((vj >> 1) * 2 + 1) ^ vx) << 4) + (vj & 1) * 8;
;   bf16x8 sk0, sk1, sv0, sv1;
;   char* kbuf = stg; char* vbuf = stg + 32768;
;     ...
;   f32x16 o[4];
; #pragma unroll
;   for (int d0 = 0; d0 < 4; ++d0)
; #pragma unroll
;     for (int r = 0; r < 16; ++r) o[d0][r] = 0.f;
;   float m_reg = -1e30f, l_reg = 0.f;
;   const int xq = (l31 >> 1) & 7;
;   f32x16 pA0, pA1, pB0, pB1;
;   K_LOAD(0); V_LOAD(0);
;   {
;     const bf16x8 tk0 = *(const bf16x8*)(kg + (size_t)8192), tk1 = *(const bf16x8*)(kg + (size_t)8192 + 4096);
;     K_STORE(0); V_STORE(0);
;     sk0 = tk0; sk1 = tk1; K_STORE(1);
;   }
;   __syncthreads();
;   QK_TILE(pA0, pA1, 0);
;   __syncthreads();
;     ...
;         if (threadIdx.x == 0) s_item = atomicAdd(cnt + q, 1);
;         __syncthreads();
;         const int item = s_item;
;         __syncthreads();
;         if (item >= 192) break;
;         int bh, qblk;
;         if (item < 128) { bh = q; qblk = 127 - item; }
;         else { bh = 8 + (q >> 1); qblk = 127 - 2 * (item - 128) - (q & 1); }
;         attn_item(p, l, bh, qblk, lam, osc, smem);
.LBB0_537:
	s_or_b64 exec, exec, s[8:9]
	s_waitcnt lgkmcnt(0)
	s_barrier
	ds_read_b32 v2, v173
	s_movk_i32 s8, 0xbf
	s_waitcnt lgkmcnt(0)
	s_barrier
	v_cmp_lt_i32_e32 vcc, s8, v2
	v_readfirstlane_b32 s52, v2
	s_mov_b64 s[8:9], -1
	s_cbranch_vccnz .LBB0_532
	s_lshl_b32 s9, s52, 1
	s_or_b32 s9, s9, s87
	s_sub_i32 s8, 0x7f, s52
	s_sub_i32 s9, 0x17f, s9
	s_cmpk_lt_i32 s52, 0x80
	s_cselect_b32 s72, s8, s9
	s_cselect_b32 s52, s79, s86
	s_lshl_b32 s88, s72, 1
	s_cmp_gt_u32 s52, 5
	s_cselect_b32 s53, 0x4000, 0
	s_lshl_b64 s[8:9], s[72:73], 7
	s_add_u32 s84, s8, s53
	s_addc_u32 s85, s9, 0
	s_lshl_b32 s8, s52, 7
	s_add_i32 s9, s8, 0xfffffd00
	s_cmp_lt_u32 s52, 6
	s_cselect_b32 s72, s8, s9
	s_lshl_b32 s8, s52, 22
	s_mov_b32 s9, s73
	v_lshl_add_u64 v[20:21], v[174:175], 0, s[8:9]
	v_add_co_u32_e32 v12, vcc, s35, v20
	v_lshl_add_u64 v[10:11], v[176:177], 0, s[8:9]
	s_nop 0
	v_addc_co_u32_e32 v13, vcc, 0, v21, vcc
	v_add_co_u32_e32 v14, vcc, s35, v10
	s_movk_i32 s9, 0x4000
	s_nop 0
	v_addc_co_u32_e32 v15, vcc, 0, v11, vcc
	v_add_co_u32_e32 v22, vcc, s9, v20
	s_movk_i32 s9, 0x6000
	s_nop 0
	v_addc_co_u32_e32 v23, vcc, 0, v21, vcc
	v_or_b32_e32 v24, s84, v170
	v_mov_b64_e32 v[18:19], s[28:29]
	global_load_dwordx4 v[2:5], v[20:21], off
	global_load_dwordx4 v[6:9], v[10:11], off
	v_add_co_u32_e32 v20, vcc, s9, v20
	s_movk_i32 s9, 0xa00
	v_mad_u64_u32 v[18:19], s[52:53], v24, s9, v[18:19]
	v_mad_u32_u24 v19, s85, v211, v19
	global_load_dwordx4 v[10:13], v[12:13], off
	s_nop 0
	global_load_dwordx4 v[14:17], v[14:15], off
	v_addc_co_u32_e32 v21, vcc, 0, v21, vcc
	global_load_dwordx4 v[146:149], v[22:23], off
	global_load_dwordx4 v[150:153], v[20:21], off
	v_lshl_add_u64 v[18:19], s[72:73], 1, v[18:19]
	v_mov_b32_e32 v185, v173
	v_lshl_add_u64 v[18:19], v[18:19], 0, v[184:185]
	v_mov_b32_e32 v187, v173
	v_lshl_add_u64 v[18:19], v[18:19], 0, v[186:187]
	s_mov_b32 s9, 0x1da00000
	v_add_co_u32_e32 v20, vcc, s9, v18
	s_mov_b64 s[52:53], 0x1da00400
	s_nop 0
	v_addc_co_u32_e32 v21, vcc, 0, v19, vcc
	global_load_dwordx4 v[130:133], v[20:21], off offset:1024
	v_lshl_add_u64 v[18:19], v[18:19], 0, s[52:53]
	global_load_dwordx4 v[134:137], v[18:19], off offset:32
	global_load_dwordx4 v[138:141], v[18:19], off offset:64
	global_load_dwordx4 v[142:145], v[18:19], off offset:96
	v_add_u32_e32 v185, v201, v202
	v_add_u32_e32 v187, v201, v203
	v_add_u32_e32 v215, v201, v204
	v_add_u32_e32 v216, v201, v205
	s_mov_b32 s52, 0
	s_mov_b32 s53, s52
	s_mov_b32 s54, s52
	s_mov_b32 s55, s52
	s_mov_b32 s56, s52
	s_mov_b32 s57, s52
	s_mov_b32 s58, s52
	s_mov_b32 s59, s52
	s_mov_b32 s60, s52
	s_mov_b32 s61, s52
	s_mov_b32 s62, s52
	s_mov_b32 s63, s52
	s_mov_b32 s64, s52
	s_mov_b32 s65, s52
	s_mov_b32 s66, s52
	s_mov_b32 s67, s52
	v_mov_b64_e32 v[50:51], s[52:53]
	v_mov_b64_e32 v[52:53], s[54:55]
	v_mov_b64_e32 v[54:55], s[56:57]
	v_mov_b64_e32 v[56:57], s[58:59]
	v_mov_b64_e32 v[58:59], s[60:61]
	v_mov_b64_e32 v[60:61], s[62:63]
	v_mov_b64_e32 v[62:63], s[64:65]
	v_mov_b64_e32 v[64:65], s[66:67]
	s_add_i32 s53, s88, 2
	s_add_u32 s54, s28, s8
	v_mov_b64_e32 v[34:35], v[50:51]
	v_mov_b64_e32 v[18:19], v[50:51]
	v_add_u32_e32 v217, s88, v197
	s_addc_u32 s55, s29, 0
	s_add_u32 s54, s54, 0x22a08000
	s_addc_u32 s55, s55, 0
	v_mov_b32_e32 v218, 0
	v_mov_b32_e32 v192, 0xf149f2ca
	v_mov_b64_e32 v[36:37], v[52:53]
	v_mov_b64_e32 v[38:39], v[54:55]
	v_mov_b64_e32 v[40:41], v[56:57]
	s_waitcnt vmcnt(9)
	ds_write_b128 v212, v[2:5] offset:2048
	s_waitcnt vmcnt(8)
	ds_write_b128 v253, v[6:9] offset:34816
	s_waitcnt vmcnt(7)
	ds_write_b128 v212, v[10:13] offset:6144
	s_waitcnt vmcnt(6)
	ds_write_b128 v253, v[14:17] offset:43008
	s_waitcnt vmcnt(5)
	ds_write_b128 v212, v[146:149] offset:18432
	s_waitcnt vmcnt(4)
	ds_write_b128 v212, v[150:153] offset:22528
	s_waitcnt lgkmcnt(0)
	s_barrier
	ds_read_b128 v[2:5], v185 offset:2048
	ds_read_b128 v[6:9], v185 offset:6144
	s_waitcnt vmcnt(3) lgkmcnt(1)
	v_mfma_f32_32x32x16_bf16 v[66:81], v[2:5], v[130:133], 0
	v_mov_b64_e32 v[42:43], v[58:59]
	v_mov_b64_e32 v[44:45], v[60:61]
	v_mov_b64_e32 v[46:47], v[62:63]
	v_mov_b64_e32 v[48:49], v[64:65]
	v_mov_b64_e32 v[20:21], v[52:53]
	v_mov_b64_e32 v[22:23], v[54:55]
	v_mov_b64_e32 v[24:25], v[56:57]
	s_waitcnt lgkmcnt(0)
	v_mfma_f32_32x32x16_bf16 v[82:97], v[6:9], v[130:133], 0
	ds_read_b128 v[2:5], v187 offset:2048
	ds_read_b128 v[6:9], v187 offset:6144
	v_mov_b64_e32 v[26:27], v[58:59]
	v_mov_b64_e32 v[28:29], v[60:61]
	v_mov_b64_e32 v[30:31], v[62:63]
	v_mov_b64_e32 v[32:33], v[64:65]
	s_waitcnt vmcnt(2) lgkmcnt(1)
	v_mfma_f32_32x32x16_bf16 v[66:81], v[2:5], v[134:137], v[66:81]
	ds_read_b128 v[2:5], v215 offset:2048
	s_waitcnt lgkmcnt(1)
	v_mfma_f32_32x32x16_bf16 v[82:97], v[6:9], v[134:137], v[82:97]
	ds_read_b128 v[6:9], v215 offset:6144
	s_waitcnt vmcnt(1) lgkmcnt(1)
	v_mfma_f32_32x32x16_bf16 v[66:81], v[2:5], v[138:141], v[66:81]
	ds_read_b128 v[2:5], v216 offset:2048
	s_waitcnt lgkmcnt(1)
	v_mfma_f32_32x32x16_bf16 v[82:97], v[6:9], v[138:141], v[82:97]
	ds_read_b128 v[6:9], v216 offset:6144
	s_waitcnt lgkmcnt(0)
	s_barrier
	s_waitcnt vmcnt(0)
	v_mfma_f32_32x32x16_bf16 v[66:81], v[2:5], v[142:145], v[66:81]
	v_mfma_f32_32x32x16_bf16 v[82:97], v[6:9], v[142:145], v[82:97]
	v_mov_b64_e32 v[2:3], v[50:51]
	v_mov_b64_e32 v[4:5], v[52:53]
	v_mov_b64_e32 v[6:7], v[54:55]
	v_mov_b64_e32 v[8:9], v[56:57]
	v_mov_b64_e32 v[10:11], v[58:59]
	v_mov_b64_e32 v[12:13], v[60:61]
	v_mov_b64_e32 v[14:15], v[62:63]
	v_mov_b64_e32 v[16:17], v[64:65]
	s_branch .LBB0_540

.LBB0_540:
	ds_read_b128 v[98:101], v185 offset:18432
	ds_read_b128 v[114:117], v185 offset:22528
	s_cmp_lt_u32 s52, s88
	s_cselect_b64 s[58:59], -1, 0
	s_cmp_ge_u32 s52, s88
	s_cselect_b64 s[56:57], -1, 0
	s_and_b64 vcc, exec, s[56:57]
	s_cbranch_vccnz .LBB0_542
	s_add_u32 m0, s101, 0x810
	s_nop 0
	global_load_lds_dwordx4 v180, s[54:55]
	s_add_u32 m0, s101, 0x2790
	s_nop 0
	global_load_lds_dwordx4 v180, s[54:55] offset:128
.LBB0_542:
	s_add_u32 m0, s101, 0xc810
	s_nop 0
	global_load_lds_dwordx4 v243, s[54:55]
	s_add_u32 m0, s101, 0xe810
	s_nop 0
	global_load_lds_dwordx4 v244, s[54:55]
	v_cmp_le_u32_e32 vcc, s52, v217
	s_and_saveexec_b64 s[8:9], vcc
	s_cbranch_execz .LBB0_548
	s_waitcnt lgkmcnt(1)
	v_mfma_f32_32x32x16_bf16 v[98:113], v[98:101], v[130:133], 0
	ds_read_b128 v[118:121], v187 offset:18432
	ds_read_b128 v[220:223], v187 offset:22528
	s_waitcnt lgkmcnt(1)
	v_mfma_f32_32x32x16_bf16 v[98:113], v[118:121], v[134:137], v[98:113]
	ds_read_b128 v[118:121], v215 offset:18432
	s_waitcnt lgkmcnt(0)
	v_mfma_f32_32x32x16_bf16 v[98:113], v[118:121], v[138:141], v[98:113]
	ds_read_b128 v[118:121], v216 offset:18432
	s_waitcnt lgkmcnt(0)
	v_mfma_f32_32x32x16_bf16 v[98:113], v[118:121], v[142:145], v[98:113]
	v_max_f32_e32 v118, v67, v67
	v_max_f32_e32 v119, v66, v66
	v_max_f32_e32 v118, v119, v118
	v_max3_f32 v118, v118, v68, v69
	v_max3_f32 v118, v118, v70, v71
	v_max3_f32 v118, v118, v72, v73
	v_max3_f32 v118, v118, v74, v75
	v_max3_f32 v118, v118, v76, v77
	v_max3_f32 v118, v118, v78, v79
	v_max3_f32 v219, v118, v80, v81
	v_mfma_f32_32x32x16_bf16 v[114:129], v[114:117], v[130:133], 0
	v_max3_f32 v219, v219, v82, v83
	v_max3_f32 v219, v219, v84, v85
	v_max3_f32 v219, v219, v86, v87
	v_max3_f32 v219, v219, v88, v89
	v_max3_f32 v219, v219, v90, v91
	v_max3_f32 v219, v219, v92, v93
	v_max3_f32 v219, v219, v94, v95
	v_max3_f32 v219, v219, v96, v97
	v_mfma_f32_32x32x16_bf16 v[114:129], v[220:223], v[134:137], v[114:129]
	v_mov_b32_e32 v220, v219
	s_nop 1
	v_permlane32_swap_b32_e32 v219, v220
	v_max_f32_e32 v220, v220, v220
	v_max_f32_e32 v219, v219, v219
	v_max_f32_e32 v219, v219, v220
	v_sub_f32_e32 v220, v219, v192
	v_cmp_ge_f32_e32 vcc, s36, v220
	s_cmp_eq_u64 vcc, exec
	v_max_f32_e32 v220, v192, v192
	s_cselect_b64 vcc, -1, 0
	v_max_f32_e32 v219, v220, v219
	v_cndmask_b32_e32 v219, v219, v192, vcc
	v_sub_f32_e32 v192, v192, v219
	v_mul_f32_e32 v192, 0x3e38aa3b, v192
	v_exp_f32_e32 v220, v192
	v_mul_f32_e32 v192, 0xbe38aa3b, v219
	v_pk_fma_f32 v[96:97], v[96:97], s[78:79], v[192:193] op_sel_hi:[1,0,0]
	ds_read_b128 v[224:227], v215 offset:22528
	v_pk_fma_f32 v[86:87], v[86:87], s[78:79], v[192:193] op_sel_hi:[1,0,0]
	v_pk_fma_f32 v[88:89], v[88:89], s[78:79], v[192:193] op_sel_hi:[1,0,0]
	v_pk_fma_f32 v[90:91], v[90:91], s[78:79], v[192:193] op_sel_hi:[1,0,0]
	v_pk_fma_f32 v[92:93], v[92:93], s[78:79], v[192:193] op_sel_hi:[1,0,0]
	v_pk_fma_f32 v[94:95], v[94:95], s[78:79], v[192:193] op_sel_hi:[1,0,0]
	ds_read_b128 v[162:165], v216 offset:22528
	v_pk_fma_f32 v[84:85], v[84:85], s[78:79], v[192:193] op_sel_hi:[1,0,0]
	s_waitcnt lgkmcnt(1)
	v_mfma_f32_32x32x16_bf16 v[114:129], v[224:227], v[138:141], v[114:129]
	v_fma_f32 v66, v66, s78, v192
	v_fma_f32 v67, v67, s78, v192
	v_fma_f32 v68, v68, s78, v192
	v_fma_f32 v69, v69, s78, v192
	v_exp_f32_e32 v66, v66
	v_exp_f32_e32 v67, v67
	v_exp_f32_e32 v68, v68
	v_exp_f32_e32 v69, v69
	v_pk_fma_f32 v[70:71], v[70:71], s[78:79], v[192:193] op_sel_hi:[1,0,0]
	v_pk_add_f32 v[222:223], v[66:67], 0 op_sel_hi:[1,0]
	v_exp_f32_e32 v70, v70
	v_exp_f32_e32 v71, v71
	v_pk_add_f32 v[222:223], v[68:69], v[222:223]
	v_pk_fma_f32 v[72:73], v[72:73], s[78:79], v[192:193] op_sel_hi:[1,0,0]
	v_exp_f32_e32 v84, v84
	v_pk_add_f32 v[222:223], v[70:71], v[222:223]
	v_exp_f32_e32 v72, v72
	v_exp_f32_e32 v73, v73
	s_waitcnt lgkmcnt(0)
	v_mfma_f32_32x32x16_bf16 v[114:129], v[162:165], v[142:145], v[114:129]
	v_fma_f32 v74, v74, s78, v192
	v_fma_f32 v75, v75, s78, v192
	v_fma_f32 v76, v76, s78, v192
	v_fma_f32 v77, v77, s78, v192
	v_exp_f32_e32 v74, v74
	v_exp_f32_e32 v75, v75
	v_exp_f32_e32 v76, v76
	v_exp_f32_e32 v77, v77
	v_pk_fma_f32 v[78:79], v[78:79], s[78:79], v[192:193] op_sel_hi:[1,0,0]
	v_pk_fma_f32 v[80:81], v[80:81], s[78:79], v[192:193] op_sel_hi:[1,0,0]
	v_exp_f32_e32 v78, v78
	v_exp_f32_e32 v79, v79
	v_pk_add_f32 v[222:223], v[72:73], v[222:223]
	v_exp_f32_e32 v80, v80
	v_exp_f32_e32 v81, v81
	v_pk_fma_f32 v[82:83], v[82:83], s[78:79], v[192:193] op_sel_hi:[1,0,0]
	v_pk_add_f32 v[222:223], v[74:75], v[222:223]
	v_exp_f32_e32 v82, v82
	v_exp_f32_e32 v83, v83
	v_pk_add_f32 v[222:223], v[76:77], v[222:223]
	v_exp_f32_e32 v85, v85
	v_pk_add_f32 v[222:223], v[78:79], v[222:223]
	v_exp_f32_e32 v86, v86
	v_exp_f32_e32 v87, v87
	v_pk_add_f32 v[222:223], v[80:81], v[222:223]
	v_exp_f32_e32 v88, v88
	v_exp_f32_e32 v89, v89
	v_pk_add_f32 v[162:163], v[82:83], v[222:223]
	v_exp_f32_e32 v90, v90
	v_exp_f32_e32 v91, v91
	v_pk_add_f32 v[162:163], v[84:85], v[162:163]
	v_exp_f32_e32 v92, v92
	v_exp_f32_e32 v93, v93
	v_pk_add_f32 v[162:163], v[86:87], v[162:163]
	v_exp_f32_e32 v94, v94
	v_exp_f32_e32 v95, v95
	v_pk_add_f32 v[162:163], v[88:89], v[162:163]
	v_exp_f32_e32 v96, v96
	v_exp_f32_e32 v97, v97
	v_pk_add_f32 v[162:163], v[90:91], v[162:163]
	s_nop 0
	v_pk_add_f32 v[162:163], v[92:93], v[162:163]
	s_nop 0
	v_pk_add_f32 v[162:163], v[94:95], v[162:163]
	s_nop 0
	v_pk_add_f32 v[162:163], v[96:97], v[162:163]
	s_nop 0
	v_pk_add_f32 v[162:163], v[162:163], v[162:163] op_sel:[0,1] op_sel_hi:[1,0]
	s_nop 0
	v_mov_b32_e32 v163, v162
	s_nop 1
	v_permlane32_swap_b32_e32 v162, v163
	s_cbranch_vccnz .LBB0_547
	s_waitcnt lgkmcnt(0)
	s_and_saveexec_b64 s[60:61], s[2:3]
	ds_write_b32 v207, v220
	s_or_b64 exec, exec, s[60:61]
	s_waitcnt lgkmcnt(0)
	v_add_u32_e32 v164, v206, v194
	ds_read_b128 v[222:225], v164 offset:96
	ds_read_b128 v[226:229], v164 offset:64
	ds_read_b128 v[230:233], v164 offset:32
	ds_read_b128 v[234:237], v164
	s_waitcnt lgkmcnt(0)
	s_waitcnt lgkmcnt(3)
	v_pk_mul_f32 v[62:63], v[62:63], v[222:223]
	s_waitcnt lgkmcnt(2)
	v_pk_mul_f32 v[58:59], v[58:59], v[226:227]
	s_waitcnt lgkmcnt(1)
	v_pk_mul_f32 v[54:55], v[54:55], v[230:231]
	v_pk_mul_f32 v[64:65], v[64:65], v[224:225]
	v_pk_mul_f32 v[60:61], v[60:61], v[228:229]
	v_pk_mul_f32 v[56:57], v[56:57], v[232:233]
	s_waitcnt lgkmcnt(0)
	v_pk_mul_f32 v[52:53], v[52:53], v[236:237]
	v_pk_mul_f32 v[50:51], v[50:51], v[234:235]
	v_pk_mul_f32 v[46:47], v[46:47], v[222:223]
	v_pk_mul_f32 v[42:43], v[42:43], v[226:227]
	v_pk_mul_f32 v[38:39], v[38:39], v[230:231]
	v_pk_mul_f32 v[48:49], v[48:49], v[224:225]
	v_pk_mul_f32 v[44:45], v[44:45], v[228:229]
	v_pk_mul_f32 v[40:41], v[40:41], v[232:233]
	v_pk_mul_f32 v[36:37], v[36:37], v[236:237]
	v_pk_mul_f32 v[34:35], v[34:35], v[234:235]
	v_pk_mul_f32 v[30:31], v[30:31], v[222:223]
	v_pk_mul_f32 v[26:27], v[26:27], v[226:227]
	v_pk_mul_f32 v[22:23], v[22:23], v[230:231]
	v_pk_mul_f32 v[32:33], v[32:33], v[224:225]
	v_pk_mul_f32 v[28:29], v[28:29], v[228:229]
	v_pk_mul_f32 v[24:25], v[24:25], v[232:233]
	v_pk_mul_f32 v[20:21], v[20:21], v[236:237]
	v_pk_mul_f32 v[18:19], v[18:19], v[234:235]
	v_pk_mul_f32 v[14:15], v[14:15], v[222:223]
	v_pk_mul_f32 v[10:11], v[10:11], v[226:227]
	v_pk_mul_f32 v[6:7], v[6:7], v[230:231]
	v_pk_mul_f32 v[16:17], v[16:17], v[224:225]
	v_pk_mul_f32 v[12:13], v[12:13], v[228:229]
	v_pk_mul_f32 v[8:9], v[8:9], v[232:233]
	v_pk_mul_f32 v[4:5], v[4:5], v[236:237]
	v_pk_mul_f32 v[2:3], v[2:3], v[234:235]

; DEVI void attn_item(const Params& p, const int l, const int bh, const int qblk, const float lam, const float osc, char* smem) {
;     ...
;   for (int kt = 0; kt < nkt; kt += 2) {
;     ATT_ITER(kt, pA0, pA1, pB0, pB1);
;     ATT_ITER(kt + 1, pB0, pB1, pA0, pA1);
.LBB0_550:
	s_add_i32 s60, s52, 3
	s_cmp_lt_u32 s60, s53
	s_cselect_b64 s[58:59], -1, 0
	s_cmp_ge_u32 s60, s53
	s_waitcnt vmcnt(0)
	s_waitcnt lgkmcnt(0)
	s_barrier
	ds_read_b128 v[66:69], v185 offset:2048
	ds_read_b128 v[82:85], v185 offset:6144
	s_cbranch_scc0 .LBB0_555
	s_and_b64 vcc, exec, s[8:9]
	s_cbranch_vccz .LBB0_556

.LBB0_555:
	s_add_u32 m0, s101, 0x4810
	s_nop 0
	global_load_lds_dwordx4 v242, s[54:55]
	s_add_u32 m0, s101, 0x6790
	s_nop 0
	global_load_lds_dwordx4 v242, s[54:55] offset:128
	s_and_b64 vcc, exec, s[8:9]
	s_cbranch_vccnz .LBB0_552
.LBB0_556:
	s_add_u32 m0, s101, 0x8810
	s_nop 0
	global_load_lds_dwordx4 v245, s[54:55]
	s_add_u32 m0, s101, 0xa810
	s_nop 0
	global_load_lds_dwordx4 v246, s[54:55]
	v_cmp_lt_u32_e32 vcc, s52, v217
	s_and_saveexec_b64 s[60:61], vcc
	s_cbranch_execz .LBB0_553
.LBB0_557:
	s_waitcnt lgkmcnt(1)
	v_mfma_f32_32x32x16_bf16 v[66:81], v[66:69], v[130:133], 0
	ds_read_b128 v[86:89], v187 offset:2048
	ds_read_b128 v[188:191], v187 offset:6144
	s_waitcnt lgkmcnt(1)
	v_mfma_f32_32x32x16_bf16 v[66:81], v[86:89], v[134:137], v[66:81]
	ds_read_b128 v[86:89], v215 offset:2048
	s_waitcnt lgkmcnt(0)
	v_mfma_f32_32x32x16_bf16 v[66:81], v[86:89], v[138:141], v[66:81]
	ds_read_b128 v[86:89], v216 offset:2048
	s_waitcnt lgkmcnt(0)
	v_mfma_f32_32x32x16_bf16 v[66:81], v[86:89], v[142:145], v[66:81]
	v_max_f32_e32 v86, v99, v99
	v_max_f32_e32 v87, v98, v98
	v_max_f32_e32 v86, v87, v86
	v_max3_f32 v86, v86, v100, v101
	v_max3_f32 v86, v86, v102, v103
	v_max3_f32 v86, v86, v104, v105
	v_max3_f32 v86, v86, v106, v107
	v_max3_f32 v86, v86, v108, v109
	v_max3_f32 v86, v86, v110, v111
	v_max3_f32 v219, v86, v112, v113
	v_mfma_f32_32x32x16_bf16 v[82:97], v[82:85], v[130:133], 0
	v_mfma_f32_32x32x16_bf16 v[82:97], v[188:191], v[134:137], v[82:97]
	v_max3_f32 v188, v219, v114, v115
	v_max3_f32 v188, v188, v116, v117
	v_max3_f32 v188, v188, v118, v119
	v_max3_f32 v188, v188, v120, v121
	v_max3_f32 v188, v188, v122, v123
	v_max3_f32 v188, v188, v124, v125
	v_max3_f32 v188, v188, v126, v127
	v_max3_f32 v188, v188, v128, v129
	v_mov_b32_e32 v189, v188
	s_nop 1
	v_permlane32_swap_b32_e32 v188, v189
	v_max_f32_e32 v189, v189, v189
	v_max_f32_e32 v188, v188, v188
	v_max_f32_e32 v188, v188, v189
	v_sub_f32_e32 v189, v188, v192
	v_cmp_ge_f32_e32 vcc, s36, v189
	s_cmp_eq_u64 vcc, exec
	v_max_f32_e32 v189, v192, v192
	s_cselect_b64 vcc, -1, 0
	v_max_f32_e32 v188, v189, v188
	v_cndmask_b32_e32 v189, v188, v192, vcc
	v_sub_f32_e32 v188, v192, v189
	v_mul_f32_e32 v188, 0x3e38aa3b, v188
	v_exp_f32_e32 v190, v188
	v_mul_f32_e32 v188, 0xbe38aa3b, v189
	v_pk_fma_f32 v[128:129], v[128:129], s[78:79], v[188:189] op_sel_hi:[1,0,0]
	ds_read_b128 v[220:223], v215 offset:6144
	v_pk_fma_f32 v[118:119], v[118:119], s[78:79], v[188:189] op_sel_hi:[1,0,0]
	v_pk_fma_f32 v[120:121], v[120:121], s[78:79], v[188:189] op_sel_hi:[1,0,0]
	v_pk_fma_f32 v[122:123], v[122:123], s[78:79], v[188:189] op_sel_hi:[1,0,0]
	v_pk_fma_f32 v[124:125], v[124:125], s[78:79], v[188:189] op_sel_hi:[1,0,0]
	v_pk_fma_f32 v[126:127], v[126:127], s[78:79], v[188:189] op_sel_hi:[1,0,0]
	ds_read_b128 v[162:165], v216 offset:6144
	v_pk_fma_f32 v[108:109], v[108:109], s[78:79], v[188:189] op_sel_hi:[1,0,0]
	v_pk_fma_f32 v[110:111], v[110:111], s[78:79], v[188:189] op_sel_hi:[1,0,0]
	v_pk_fma_f32 v[112:113], v[112:113], s[78:79], v[188:189] op_sel_hi:[1,0,0]
	v_pk_fma_f32 v[114:115], v[114:115], s[78:79], v[188:189] op_sel_hi:[1,0,0]
	v_pk_fma_f32 v[116:117], v[116:117], s[78:79], v[188:189] op_sel_hi:[1,0,0]
	s_waitcnt lgkmcnt(1)
	v_mfma_f32_32x32x16_bf16 v[82:97], v[220:223], v[138:141], v[82:97]
	v_fma_f32 v98, v98, s78, v188
	v_fma_f32 v99, v99, s78, v188
	v_fma_f32 v100, v100, s78, v188
	v_fma_f32 v101, v101, s78, v188
	v_exp_f32_e32 v98, v98
	v_exp_f32_e32 v99, v99
	v_exp_f32_e32 v100, v100
	v_exp_f32_e32 v101, v101
	v_pk_fma_f32 v[102:103], v[102:103], s[78:79], v[188:189] op_sel_hi:[1,0,0]
	v_pk_fma_f32 v[104:105], v[104:105], s[78:79], v[188:189] op_sel_hi:[1,0,0]
	v_exp_f32_e32 v102, v102
	v_exp_f32_e32 v103, v103
	v_exp_f32_e32 v104, v104
	v_exp_f32_e32 v105, v105
	v_pk_fma_f32 v[106:107], v[106:107], s[78:79], v[188:189] op_sel_hi:[1,0,0]
	v_pk_add_f32 v[220:221], v[98:99], 0 op_sel_hi:[1,0]
	v_exp_f32_e32 v106, v106
	v_exp_f32_e32 v107, v107
	v_pk_add_f32 v[220:221], v[100:101], v[220:221]
	v_exp_f32_e32 v108, v108
	v_exp_f32_e32 v109, v109
	v_pk_add_f32 v[220:221], v[102:103], v[220:221]
	v_exp_f32_e32 v110, v110
	v_exp_f32_e32 v111, v111
	v_pk_add_f32 v[220:221], v[104:105], v[220:221]
	v_exp_f32_e32 v112, v112
	v_exp_f32_e32 v113, v113
	v_pk_add_f32 v[220:221], v[106:107], v[220:221]
	v_exp_f32_e32 v114, v114
	v_exp_f32_e32 v115, v115
	v_pk_add_f32 v[220:221], v[108:109], v[220:221]
	v_exp_f32_e32 v116, v116
	v_exp_f32_e32 v117, v117
	v_pk_add_f32 v[220:221], v[110:111], v[220:221]
	v_exp_f32_e32 v118, v118
	v_exp_f32_e32 v119, v119
	v_pk_add_f32 v[220:221], v[112:113], v[220:221]
	v_exp_f32_e32 v120, v120
	v_exp_f32_e32 v121, v121
	s_waitcnt lgkmcnt(0)
	v_mfma_f32_32x32x16_bf16 v[82:97], v[162:165], v[142:145], v[82:97]
	v_add_f32_e64 v162, v114, v220
	v_add_f32_e64 v163, v115, v221
	v_exp_f32_e32 v122, v122
	v_exp_f32_e32 v123, v123
	v_pk_add_f32 v[162:163], v[116:117], v[162:163]
	v_exp_f32_e32 v124, v124
	v_exp_f32_e32 v125, v125
	v_pk_add_f32 v[162:163], v[118:119], v[162:163]
	v_exp_f32_e32 v126, v126
	v_exp_f32_e32 v127, v127
	v_pk_add_f32 v[162:163], v[120:121], v[162:163]
	v_exp_f32_e32 v128, v128
	v_exp_f32_e32 v129, v129
	v_pk_add_f32 v[162:163], v[122:123], v[162:163]
	s_nop 0
	v_pk_add_f32 v[162:163], v[124:125], v[162:163]
	s_nop 0
	v_pk_add_f32 v[162:163], v[126:127], v[162:163]
	s_nop 0
	v_pk_add_f32 v[162:163], v[128:129], v[162:163]
	s_nop 0
	v_pk_add_f32 v[162:163], v[162:163], v[162:163] op_sel:[0,1] op_sel_hi:[1,0]
	s_nop 0
	v_mov_b32_e32 v163, v162
	s_nop 1
	v_permlane32_swap_b32_e32 v162, v163
	s_cbranch_vccnz .LBB0_561
	s_waitcnt lgkmcnt(0)
	s_and_saveexec_b64 s[62:63], s[2:3]
	ds_write_b32 v207, v190
	s_or_b64 exec, exec, s[62:63]
	s_waitcnt lgkmcnt(0)
	v_add_u32_e32 v164, v206, v194
	ds_read_b128 v[220:223], v164 offset:96
	ds_read_b128 v[224:227], v164 offset:64
	ds_read_b128 v[228:231], v164 offset:32
	ds_read_b128 v[232:235], v164
	s_waitcnt lgkmcnt(0)
	s_waitcnt lgkmcnt(3)
	v_pk_mul_f32 v[62:63], v[62:63], v[220:221]
	s_waitcnt lgkmcnt(2)
	v_pk_mul_f32 v[58:59], v[58:59], v[224:225]
	s_waitcnt lgkmcnt(1)
	v_pk_mul_f32 v[54:55], v[54:55], v[228:229]
	v_pk_mul_f32 v[64:65], v[64:65], v[222:223]
	v_pk_mul_f32 v[60:61], v[60:61], v[226:227]
	v_pk_mul_f32 v[56:57], v[56:57], v[230:231]
	s_waitcnt lgkmcnt(0)
	v_pk_mul_f32 v[52:53], v[52:53], v[234:235]
	v_pk_mul_f32 v[50:51], v[50:51], v[232:233]
	v_pk_mul_f32 v[46:47], v[46:47], v[220:221]
	v_pk_mul_f32 v[42:43], v[42:43], v[224:225]
	v_pk_mul_f32 v[38:39], v[38:39], v[228:229]
	v_pk_mul_f32 v[48:49], v[48:49], v[222:223]
	v_pk_mul_f32 v[44:45], v[44:45], v[226:227]
	v_pk_mul_f32 v[40:41], v[40:41], v[230:231]
	v_pk_mul_f32 v[36:37], v[36:37], v[234:235]
	v_pk_mul_f32 v[34:35], v[34:35], v[232:233]
	v_pk_mul_f32 v[30:31], v[30:31], v[220:221]
	v_pk_mul_f32 v[26:27], v[26:27], v[224:225]
	v_pk_mul_f32 v[22:23], v[22:23], v[228:229]
	v_pk_mul_f32 v[32:33], v[32:33], v[222:223]
	v_pk_mul_f32 v[28:29], v[28:29], v[226:227]
	v_pk_mul_f32 v[24:25], v[24:25], v[230:231]
	v_pk_mul_f32 v[20:21], v[20:21], v[234:235]
	v_pk_mul_f32 v[18:19], v[18:19], v[232:233]
	v_pk_mul_f32 v[14:15], v[14:15], v[220:221]
	v_pk_mul_f32 v[10:11], v[10:11], v[224:225]
	v_pk_mul_f32 v[6:7], v[6:7], v[228:229]
	v_pk_mul_f32 v[16:17], v[16:17], v[222:223]
	v_pk_mul_f32 v[12:13], v[12:13], v[226:227]
	v_pk_mul_f32 v[8:9], v[8:9], v[230:231]
	v_pk_mul_f32 v[4:5], v[4:5], v[234:235]
	v_pk_mul_f32 v[2:3], v[2:3], v[232:233]

; DEVI void attn_item(const Params& p, const int l, const int bh, const int qblk, const float lam, const float osc, char* smem) {
;   const int tid = threadIdx.x, wid = tid >> 6, lane = tid & 63, l31 = lane & 31, hi = lane >> 5;
;   const int b = bh / 6, h = bh % 6;
;   const int qg = wid >> 1, m = wid & 1;
;   const int nkt = 2 * qblk + 2;
;   const int my_last = 2 * qblk + (qg >> 1);
;   const u16* PBC = (const u16*)(p.ws + OFF_PBC);
;   const u16* VT = (const u16*)(p.ws + OFF_VT) + (size_t)(b * 6 + h) * 256 * 8192;
;   const u16* KT = (const u16*)(p.ws + OFF_KT) + (size_t)(b * 6 + h) * 256 * 8192;
;   const size_t tok0 = (size_t)b * SEQ_;
;   float* wsc = (float*)smem + wid * 64;
;   char* stg = smem + 2048;
;   float* obuf = (float*)(smem + 2048);
;   constexpr float C = 0.125f * 1.4426950408889634f;
;   bf16x8 qf[4];
;   {
;     const u16* qp = PBC + (tok0 + (size_t)qblk * 128 + qg * 32 + l31) * 1280 + 512 + h * 128 + m * 64 + hi * 8;
; #pragma unroll
;     for (int d0 = 0; d0 < 4; ++d0) qf[d0] = *(const bf16x8*)(qp + d0 * 16);
;   }
;   const int kkey = tid >> 4, kch = tid & 15;
;   const u16* kg = KT + kkey * 128 + kch * 8;
;   const int klds = (kch >> 3) * 8192 + swz(kkey, kch & 7);
;   const int ve = tid >> 3, vj = tid & 7;
;   const u16* vg = VT + ve * 64 + vj * 8;
;   const int vx = (ve >> 1) & 7;
;   const int vlds0 = 16384 + ve * 128 + ((((vj >> 1) * 2 + 0) ^ vx) << 4) + (vj & 1) * 8;
;   const int vlds1 = 16384 + ve * 128 + ((((vj >> 1) * 2 + 1) ^ vx) << 4) + (vj & 1) * 8;
;     ...
;   float d1 = 0.f, d2 = 0.f;
;   for (int i = 0; i < 64; ++i) { d1 += p.in[25][l * 64 + i] * p.in[26][l * 64 + i]; d2 += p.in[27][l * 64 + i] * p.in[28][l * 64 + i]; }
;   const float lam_init = 0.8f - 0.6f * expf(-0.3f * (float)l);
;   const float lam = expf(d1) - expf(d2) + lam_init;
;   const float osc = 1.f - lam_init;
.LBB0_1303:
	s_add_u32 s2, s14, s0
	s_addc_u32 s3, s15, s1
	global_load_dwordx4 v[6:9], v4, s[2:3] offset:256
	global_load_dwordx4 v[10:13], v4, s[2:3] offset:272
	s_add_u32 s2, s16, s0
	s_addc_u32 s3, s17, s1
	global_load_dwordx4 v[14:17], v4, s[2:3] offset:256
	global_load_dwordx4 v[18:21], v4, s[2:3] offset:272
	s_add_u32 s2, s18, s0
	s_addc_u32 s3, s19, s1
	global_load_dwordx4 v[22:25], v4, s[2:3] offset:256
	global_load_dwordx4 v[26:29], v4, s[2:3] offset:272
	s_add_u32 s2, s20, s0
	s_addc_u32 s3, s21, s1
	global_load_dwordx4 v[30:33], v4, s[2:3] offset:256
	global_load_dwordx4 v[34:37], v4, s[2:3] offset:272
	s_add_u32 s0, s0, 32
	s_addc_u32 s1, s1, 0
	s_cmpk_eq_i32 s0, 0x100
	s_waitcnt vmcnt(0)
	v_mov_b32_e32 v38, v6
	v_mov_b32_e32 v6, v8
	v_mov_b32_e32 v8, v10
	v_mov_b32_e32 v10, v12
	v_mov_b32_e32 v12, v14
	v_mov_b32_e32 v14, v16
	v_mov_b32_e32 v39, v22
	v_mov_b32_e32 v22, v7
	v_mov_b32_e32 v7, v24
	v_mov_b32_e32 v24, v9
	v_mov_b32_e32 v9, v26
	v_mov_b32_e32 v26, v11
	v_mov_b32_e32 v11, v28
	v_mov_b32_e32 v28, v13
	v_mov_b32_e32 v13, v30
	v_mov_b32_e32 v30, v15
	v_pk_fma_f32 v[2:3], v[38:39], v[12:13], v[2:3]
	v_mov_b32_e32 v15, v32
	v_pk_fma_f32 v[2:3], v[22:23], v[30:31], v[2:3]
	v_mov_b32_e32 v32, v17
	v_pk_fma_f32 v[2:3], v[6:7], v[14:15], v[2:3]
	v_mov_b32_e32 v16, v18
	v_mov_b32_e32 v17, v34
	v_pk_fma_f32 v[2:3], v[24:25], v[32:33], v[2:3]
	v_mov_b32_e32 v34, v19
	v_pk_fma_f32 v[2:3], v[8:9], v[16:17], v[2:3]
	v_mov_b32_e32 v18, v20
	v_mov_b32_e32 v19, v36
	v_pk_fma_f32 v[2:3], v[26:27], v[34:35], v[2:3]
	v_mov_b32_e32 v36, v21
	v_pk_fma_f32 v[2:3], v[10:11], v[18:19], v[2:3]
	s_nop 0
	v_pk_fma_f32 v[2:3], v[28:29], v[36:37], v[2:3]
	s_cbranch_scc0 .LBB0_1303
	v_mul_f32_e32 v4, 0x3fb8aa3b, v2
	s_mov_b32 s0, 0x3fb8aa3b
	v_rndne_f32_e32 v5, v4
	v_sub_f32_e32 v6, v4, v5
	v_fma_f32 v4, v2, s0, -v4
	v_fmac_f32_e32 v4, 0x32a5705f, v2
	v_add_f32_e32 v4, v6, v4
	v_exp_f32_e32 v4, v4
	v_cvt_i32_f32_e32 v5, v5
	s_mov_b32 s1, 0xc2ce8ed0
	v_cmp_ngt_f32_e32 vcc, s1, v2
	s_mov_b32 s2, 0x42b17218
	v_ldexp_f32 v4, v4, v5
	v_mul_f32_e32 v5, 0x3fb8aa3b, v3
	v_rndne_f32_e32 v6, v5
	v_sub_f32_e32 v7, v5, v6
	v_fma_f32 v5, v3, s0, -v5
	v_fmac_f32_e32 v5, 0x32a5705f, v3
	v_add_f32_e32 v5, v7, v5
	v_exp_f32_e32 v5, v5
	v_cvt_i32_f32_e32 v6, v6
	v_cndmask_b32_e32 v4, 0, v4, vcc
	v_mov_b32_e32 v7, 0x7f800000
	v_cmp_nlt_f32_e32 vcc, s2, v2
	v_and_b32_e32 v163, 0x3ff, v0
	v_lshlrev_b32_e32 v9, 7, v42
	v_cndmask_b32_e32 v2, v7, v4, vcc
	v_ldexp_f32 v4, v5, v6
	v_cmp_ngt_f32_e32 vcc, s1, v3
	v_bfe_u32 v192, v163, 5, 1
	v_and_b32_e32 v13, 6, v0
	v_cndmask_b32_e32 v4, 0, v4, vcc
	v_cmp_nlt_f32_e32 vcc, s2, v3
	s_movk_i32 s2, 0x3ff
	v_and_b32_e32 v162, 31, v0
	v_cndmask_b32_e32 v3, v7, v4, vcc
	v_sub_f32_e32 v2, v2, v3
	v_bfe_u32 v3, v0, 5, 5
	v_bitop3_b32 v6, v3, v0, s2 bitop3:0x78
	v_lshlrev_b32_e32 v6, 4, v6
	v_lshl_or_b32 v11, v163, 10, v6
	s_movk_i32 s2, 0x2070
	v_and_or_b32 v11, v11, s2, v9
	v_bfe_u32 v9, v0, 1, 3
	v_bitop3_b32 v3, v3, v9, 1 bitop3:0x6c
	v_lshlrev_b32_e32 v199, 4, v3
	v_bitop3_b32 v3, v192, v9, 2 bitop3:0x36
	v_lshlrev_b32_e32 v200, 4, v3
	v_bitop3_b32 v3, v192, v9, 4 bitop3:0x36
	v_bfe_u32 v164, v0, 2, 8
	v_lshlrev_b32_e32 v10, 3, v163
	v_lshlrev_b32_e32 v16, 4, v163
	v_bitop3_b32 v14, v42, v13, 7 bitop3:0x6c
	v_lshlrev_b32_e32 v201, 4, v3
	v_bitop3_b32 v3, v192, v9, 6 bitop3:0x36
	v_and_b32_e32 v8, 0x60, v164
	v_mov_b32_e32 v169, 0
	v_bfe_u32 v12, v163, 4, 3
	v_and_b32_e32 v6, 0x1f80, v16
	v_lshlrev_b32_e32 v14, 4, v14
	v_and_b32_e32 v195, 8, v10
	v_lshlrev_b32_e32 v202, 4, v3
	v_lshlrev_b32_e32 v196, 2, v162
	v_and_b32_e32 v3, 64, v163
	v_lshlrev_b32_e32 v168, 8, v42
	v_bfe_u32 v5, v163, 6, 1
	v_and_b32_e32 v7, 0x1c0, v0
	v_bitop3_b32 v10, v13, v12, 1 bitop3:0x36
	v_or3_b32 v17, v14, v6, v195
	v_lshl_add_u32 v197, v162, 7, 16
	v_cmp_ne_u32_e64 s[6:7], 0, v3
	v_lshl_or_b32 v3, v192, 2, v8
	v_add_u32_e32 v167, 16, v196
	s_movk_i32 s8, 0x240
	v_lshl_add_u64 v[12:13], s[28:29], 0, v[168:169]
	v_and_b32_e32 v14, 0xf0, v16
	v_mov_b32_e32 v15, v169
	v_add_f32_e32 v193, 0x3eb60549, v2
	v_lshlrev_b32_e32 v2, 6, v5
	v_lshlrev_b32_e32 v10, 4, v10
	v_lshl_add_u32 v198, v5, 13, v197
	v_lshl_add_u32 v203, v7, 2, 16
	v_cmp_eq_u32_e64 s[4:5], 0, v5
	v_mad_u32_u24 v205, v3, s8, v167
	v_and_b32_e32 v3, 3, v0
	v_mad_u32_u24 v5, v164, s8, 16
	v_lshl_add_u64 v[12:13], v[12:13], 0, v[14:15]
	s_mov_b64 s[8:9], 0x22a00000
	v_mov_b32_e32 v7, v169
	v_or_b32_e32 v166, v8, v162
	v_or3_b32 v18, v10, v6, v195
	v_lshlrev_b32_e32 v8, 4, v3
	v_lshlrev_b32_e32 v10, 2, v3
	v_lshl_add_u64 v[170:171], v[12:13], 0, s[8:9]
	v_lshl_add_u64 v[12:13], s[28:29], 0, v[6:7]
	v_and_b32_e32 v14, 0x70, v16
	v_and_b32_e32 v3, 15, v0
	s_add_u32 s10, s28, 0x3dd80024
	v_lshlrev_b32_e32 v4, 3, v192
	v_lshl_add_u64 v[12:13], v[12:13], 0, v[14:15]
	s_mov_b64 s[8:9], 0x25a00000
	v_mov_b32_e32 v9, v169
	v_lshl_or_b32 v176, v3, 4, v168
	v_and_b32_e32 v3, 7, v0
	v_lshlrev_b32_e32 v180, 1, v2
	v_mbcnt_lo_u32_b32 v2, -1, 0
	s_mov_b32 s15, 0
	s_addc_u32 s19, s29, 0
	v_cmp_eq_u32_e64 s[0:1], 0, v163
	v_bfe_u32 v194, v0, 8, 2
	v_cmp_eq_u32_e64 s[2:3], 0, v192
	v_add_u32_e32 v204, v203, v196
	v_lshlrev_b32_e32 v191, 4, v192
	v_mov_b32_e32 v165, v169
	v_lshl_add_u64 v[172:173], v[12:13], 0, s[8:9]
	v_lshl_add_u64 v[174:175], s[22:23], 0, v[8:9]
	v_mov_b32_e32 v177, v169
	v_lshl_or_b32 v178, v3, 4, v6
	v_mov_b32_e32 v179, v169
	s_movk_i32 s34, 0xbf
	s_movk_i32 s35, 0x4000
	s_movk_i32 s36, 0xa00
	v_lshlrev_b32_e32 v182, 1, v4
	s_mov_b64 s[16:17], 0x1da00400
	s_mov_b32 s37, 0x1da00000
	s_movk_i32 s68, 0x2000
	s_movk_i32 s69, 0x6000
	s_mov_b32 s70, 0x42800000
	s_mov_b32 s18, 0x3e38aa3b
	v_add_u32_e32 v206, v5, v8
	v_mov_b32_e32 v207, 0x3727c5ac
	s_mov_b32 s71, 0x800000
	v_lshlrev_b32_e32 v168, 1, v10
	s_mov_b64 s[20:21], 0xba00a00
	s_mov_b32 s72, 0xba00000
	v_mov_b32_e32 v208, 0xa00
	v_add_u32_e32 v209, 16, v11
	v_add_u32_e32 v210, 16, v17
	v_add_u32_e32 v211, 16, v18
	v_mbcnt_hi_u32_b32 v190, -1, v2
	s_mov_b32 s73, 0
	v_lshrrev_b32_e32 v176, 3, v0
	v_bfe_u32 v177, v0, 4, 3
	v_and_b32_e32 v184, 7, v0
	v_xor_b32_e32 v177, v184, v177
	v_lshlrev_b32_e32 v176, 8, v176
	v_lshl_or_b32 v176, v177, 4, v176
	v_mov_b32_e32 v177, 0
	v_readfirstlane_b32 s101, v0
	s_lshr_b32 s101, s101, 6
	s_lshl_b32 s101, s101, 10
	v_lshrrev_b32_e32 v253, 3, v0
	v_bfe_u32 v186, v0, 4, 3
	v_and_b32_e32 v187, 7, v0
	v_xor_b32_e32 v186, v187, v186
	v_lshlrev_b32_e32 v253, 7, v253
	v_lshl_or_b32 v178, v186, 4, v253
	v_mov_b32_e32 v179, 0
	v_add_u32_e32 v253, 16, v178
	v_add_u32_e32 v242, 0x4000, v176
	v_add_u32_e32 v243, 0x2ffc000, v178
	v_add_u32_e32 v244, 0x2ffe000, v178
	v_add_u32_e32 v245, 0x3000000, v178
	v_add_u32_e32 v246, 0x3002000, v178
	s_branch .LBB0_1306

; #define K_LOAD(kt) do { sk0 = *(const bf16x8*)(kg + (size_t)(kt) * 8192); sk1 = *(const bf16x8*)(kg + (size_t)(kt) * 8192 + 4096); } while (0)
; #define V_LOAD(kt) do { sv0 = *(const bf16x8*)(vg + (size_t)(kt) * 8192); sv1 = *(const bf16x8*)(vg + (size_t)(kt) * 8192 + 4096); } while (0)
; #define K_STORE(bi) do { char* s_ = kbuf + (bi) * 16384; *(bf16x8*)(s_ + klds) = sk0; *(bf16x8*)(s_ + klds + 4096) = sk1; } while (0)
; DEVI void attn_item(const Params& p, const int l, const int bh, const int qblk, const float lam, const float osc, char* smem) {
;     ...
;   bf16x8 qf[4];
;   {
;     const u16* qp = PBC + (tok0 + (size_t)qblk * 128 + qg * 32 + l31) * 1280 + 512 + h * 128 + m * 64 + hi * 8;
; #pragma unroll
;     for (int d0 = 0; d0 < 4; ++d0) qf[d0] = *(const bf16x8*)(qp + d0 * 16);
;   }
;   const int kkey = tid >> 4, kch = tid & 15;
;   const u16* kg = KT + kkey * 128 + kch * 8;
;   const int klds = (kch >> 3) * 8192 + swz(kkey, kch & 7);
;   const int ve = tid >> 3, vj = tid & 7;
;   const u16* vg = VT + ve * 64 + vj * 8;
;   const int vx = (ve >> 1) & 7;
;   const int vlds0 = 16384 + ve * 128 + ((((vj >> 1) * 2 + 0) ^ vx) << 4) + (vj & 1) * 8;
;   const int vlds1 = 16384 + ve * 128 + ((((vj >> 1) * 2 + 1) ^ vx) << 4) + (vj & 1) * 8;
;   bf16x8 sk0, sk1, sv0, sv1;
;   char* kbuf = stg; char* vbuf = stg + 32768;
;     ...
;   f32x16 o[4];
; #pragma unroll
;   for (int d0 = 0; d0 < 4; ++d0)
; #pragma unroll
;     for (int r = 0; r < 16; ++r) o[d0][r] = 0.f;
;   float m_reg = -1e30f, l_reg = 0.f;
;   const int xq = (l31 >> 1) & 7;
;   f32x16 pA0, pA1, pB0, pB1;
;   K_LOAD(0); V_LOAD(0);
;   {
;     const bf16x8 tk0 = *(const bf16x8*)(kg + (size_t)8192), tk1 = *(const bf16x8*)(kg + (size_t)8192 + 4096);
;     K_STORE(0); V_STORE(0);
;     sk0 = tk0; sk1 = tk1; K_STORE(1);
;   }
;   __syncthreads();
;   QK_TILE(pA0, pA1, 0);
;   __syncthreads();
;     ...
;         if (threadIdx.x == 0) s_item = atomicAdd(cnt + q, 1);
;         __syncthreads();
;         const int item = s_item;
;         __syncthreads();
;         if (item >= 192) break;
;         int bh, qblk;
;         if (item < 128) { bh = q; qblk = 127 - item; }
;         else { bh = 8 + (q >> 1); qblk = 127 - 2 * (item - 128) - (q & 1); }
;         attn_item(p, l, bh, qblk, lam, osc, smem);
.LBB0_1313:
	s_or_b64 exec, exec, s[8:9]
	s_waitcnt lgkmcnt(0)
	s_barrier
	ds_read_b32 v2, v169
	s_mov_b64 s[8:9], -1
	s_waitcnt lgkmcnt(0)
	s_barrier
	v_cmp_lt_i32_e32 vcc, s34, v2
	v_readfirstlane_b32 s14, v2
	s_cbranch_vccnz .LBB0_1308
	s_lshl_b32 s9, s14, 1
	s_or_b32 s9, s9, s76
	s_sub_i32 s8, 0x7f, s14
	s_sub_i32 s9, 0x17f, s9
	s_cmpk_lt_i32 s14, 0x80
	s_cselect_b32 s14, s8, s9
	s_cselect_b32 s40, s74, s75
	s_lshl_b32 s77, s14, 1
	s_cmp_gt_u32 s40, 5
	s_cselect_b32 s38, 0x4000, 0
	s_lshl_b64 s[8:9], s[14:15], 7
	s_add_u32 s38, s8, s38
	s_addc_u32 s39, s9, 0
	s_lshl_b32 s8, s40, 7
	s_add_i32 s9, s8, 0xfffffd00
	s_cmp_lt_u32 s40, 6
	s_cselect_b32 s14, s8, s9
	s_lshl_b32 s8, s40, 22
	s_mov_b32 s9, s15
	v_lshl_add_u64 v[20:21], v[170:171], 0, s[8:9]
	v_add_co_u32_e32 v12, vcc, s68, v20
	v_lshl_add_u64 v[10:11], v[172:173], 0, s[8:9]
	s_nop 0
	v_addc_co_u32_e32 v13, vcc, 0, v21, vcc
	v_add_co_u32_e32 v14, vcc, s68, v10
	v_or_b32_e32 v24, s38, v166
	s_nop 0
	v_addc_co_u32_e32 v15, vcc, 0, v11, vcc
	v_mov_b64_e32 v[18:19], s[28:29]
	v_add_co_u32_e32 v22, vcc, s35, v20
	v_mad_u64_u32 v[18:19], s[40:41], v24, s36, v[18:19]
	s_nop 0
	v_addc_co_u32_e32 v23, vcc, 0, v21, vcc
	global_load_dwordx4 v[2:5], v[20:21], off
	global_load_dwordx4 v[6:9], v[10:11], off
	v_add_co_u32_e32 v20, vcc, s69, v20
	v_mad_u32_u24 v19, s39, v208, v19
	global_load_dwordx4 v[10:13], v[12:13], off
	s_nop 0
	global_load_dwordx4 v[14:17], v[14:15], off
	v_addc_co_u32_e32 v21, vcc, 0, v21, vcc
	global_load_dwordx4 v[146:149], v[22:23], off
	global_load_dwordx4 v[150:153], v[20:21], off
	v_lshl_add_u64 v[18:19], s[14:15], 1, v[18:19]
	v_mov_b32_e32 v181, v169
	v_lshl_add_u64 v[18:19], v[18:19], 0, v[180:181]
	v_mov_b32_e32 v183, v169
	v_lshl_add_u64 v[18:19], v[18:19], 0, v[182:183]
	v_add_co_u32_e32 v20, vcc, s37, v18
	v_add_u32_e32 v181, v198, v199
	s_nop 0
	v_addc_co_u32_e32 v21, vcc, 0, v19, vcc
	global_load_dwordx4 v[130:133], v[20:21], off offset:1024
	v_lshl_add_u64 v[18:19], v[18:19], 0, s[16:17]
	global_load_dwordx4 v[134:137], v[18:19], off offset:32
	global_load_dwordx4 v[138:141], v[18:19], off offset:64
	global_load_dwordx4 v[142:145], v[18:19], off offset:96
	v_add_u32_e32 v183, v198, v200
	v_add_u32_e32 v212, v198, v201
	v_add_u32_e32 v213, v198, v202
	s_mov_b32 s52, 0
	s_mov_b32 s53, s52
	s_mov_b32 s54, s52
	s_mov_b32 s55, s52
	s_mov_b32 s56, s52
	s_mov_b32 s57, s52
	s_mov_b32 s58, s52
	s_mov_b32 s59, s52
	s_mov_b32 s60, s52
	s_mov_b32 s61, s52
	s_mov_b32 s62, s52
	s_mov_b32 s63, s52
	s_mov_b32 s64, s52
	s_mov_b32 s65, s52
	s_mov_b32 s66, s52
	s_mov_b32 s67, s52
	v_mov_b64_e32 v[50:51], s[52:53]
	v_mov_b64_e32 v[52:53], s[54:55]
	v_mov_b64_e32 v[54:55], s[56:57]
	v_mov_b64_e32 v[56:57], s[58:59]
	v_mov_b64_e32 v[58:59], s[60:61]
	v_mov_b64_e32 v[60:61], s[62:63]
	v_mov_b64_e32 v[62:63], s[64:65]
	v_mov_b64_e32 v[64:65], s[66:67]
	s_add_i32 s53, s77, 2
	s_add_u32 s40, s28, s8
	v_mov_b64_e32 v[34:35], v[50:51]
	v_mov_b64_e32 v[18:19], v[50:51]
	v_add_u32_e32 v214, s77, v194
	s_addc_u32 s41, s29, 0
	s_add_u32 s40, s40, 0x22a08000
	s_addc_u32 s41, s41, 0
	v_mov_b32_e32 v215, 0
	v_mov_b32_e32 v188, 0xf149f2ca
	v_mov_b64_e32 v[36:37], v[52:53]
	v_mov_b64_e32 v[38:39], v[54:55]
	v_mov_b64_e32 v[40:41], v[56:57]
	v_mov_b64_e32 v[42:43], v[58:59]
	v_mov_b64_e32 v[44:45], v[60:61]
	v_mov_b64_e32 v[46:47], v[62:63]
	v_mov_b64_e32 v[48:49], v[64:65]
	v_mov_b64_e32 v[20:21], v[52:53]
	s_waitcnt vmcnt(9)
	ds_write_b128 v209, v[2:5] offset:2048
	s_waitcnt vmcnt(8)
	ds_write_b128 v253, v[6:9] offset:34816
	s_waitcnt vmcnt(7)
	ds_write_b128 v209, v[10:13] offset:6144
	s_waitcnt vmcnt(6)
	ds_write_b128 v253, v[14:17] offset:43008
	s_waitcnt vmcnt(5)
	ds_write_b128 v209, v[146:149] offset:18432
	s_waitcnt vmcnt(4)
	ds_write_b128 v209, v[150:153] offset:22528
	s_waitcnt lgkmcnt(0)
	s_barrier
	ds_read_b128 v[2:5], v181 offset:2048
	ds_read_b128 v[6:9], v181 offset:6144
	s_waitcnt vmcnt(3) lgkmcnt(1)
	v_mfma_f32_32x32x16_bf16 v[66:81], v[2:5], v[130:133], 0
	v_mov_b64_e32 v[22:23], v[54:55]
	v_mov_b64_e32 v[24:25], v[56:57]
	v_mov_b64_e32 v[26:27], v[58:59]
	v_mov_b64_e32 v[28:29], v[60:61]
	v_mov_b64_e32 v[30:31], v[62:63]
	v_mov_b64_e32 v[32:33], v[64:65]
	s_waitcnt lgkmcnt(0)
	v_mfma_f32_32x32x16_bf16 v[98:113], v[6:9], v[130:133], 0
	ds_read_b128 v[2:5], v183 offset:2048
	ds_read_b128 v[6:9], v183 offset:6144
	s_waitcnt vmcnt(2) lgkmcnt(1)
	v_mfma_f32_32x32x16_bf16 v[66:81], v[2:5], v[134:137], v[66:81]
	ds_read_b128 v[2:5], v212 offset:2048
	s_waitcnt lgkmcnt(1)
	v_mfma_f32_32x32x16_bf16 v[98:113], v[6:9], v[134:137], v[98:113]
	ds_read_b128 v[6:9], v212 offset:6144
	s_waitcnt vmcnt(1) lgkmcnt(1)
	v_mfma_f32_32x32x16_bf16 v[66:81], v[2:5], v[138:141], v[66:81]
	ds_read_b128 v[2:5], v213 offset:2048
	s_waitcnt lgkmcnt(1)
	v_mfma_f32_32x32x16_bf16 v[98:113], v[6:9], v[138:141], v[98:113]
	ds_read_b128 v[6:9], v213 offset:6144
	s_waitcnt lgkmcnt(0)
	s_barrier
	s_waitcnt vmcnt(0)
	v_mfma_f32_32x32x16_bf16 v[66:81], v[2:5], v[142:145], v[66:81]
	v_mfma_f32_32x32x16_bf16 v[98:113], v[6:9], v[142:145], v[98:113]
	v_mov_b64_e32 v[2:3], v[50:51]
	v_mov_b64_e32 v[4:5], v[52:53]
	v_mov_b64_e32 v[6:7], v[54:55]
	v_mov_b64_e32 v[8:9], v[56:57]
	v_mov_b64_e32 v[10:11], v[58:59]
	v_mov_b64_e32 v[12:13], v[60:61]
	v_mov_b64_e32 v[14:15], v[62:63]
	v_mov_b64_e32 v[16:17], v[64:65]
	s_branch .LBB0_1316

.LBB0_1316:
	ds_read_b128 v[82:85], v181 offset:18432
	ds_read_b128 v[114:117], v181 offset:22528
	s_cmp_lt_u32 s52, s77
	s_cselect_b64 s[54:55], -1, 0
	s_cmp_ge_u32 s52, s77
	s_cselect_b64 s[42:43], -1, 0
	s_and_b64 vcc, exec, s[42:43]
	s_cbranch_vccnz .LBB0_1318
	s_add_u32 m0, s101, 0x810
	s_nop 0
	global_load_lds_dwordx4 v176, s[40:41]
	s_add_u32 m0, s101, 0x2790
	s_nop 0
	global_load_lds_dwordx4 v176, s[40:41] offset:128
.LBB0_1318:
	s_add_u32 m0, s101, 0xc810
	s_nop 0
	global_load_lds_dwordx4 v243, s[40:41]
	s_add_u32 m0, s101, 0xe810
	s_nop 0
	global_load_lds_dwordx4 v244, s[40:41]
	v_cmp_le_u32_e32 vcc, s52, v214
	s_and_saveexec_b64 s[8:9], vcc
	s_cbranch_execz .LBB0_1324
	s_waitcnt lgkmcnt(1)
	v_mfma_f32_32x32x16_bf16 v[82:97], v[82:85], v[130:133], 0
	v_max_f32_e32 v118, v67, v67
	v_max_f32_e32 v119, v66, v66
	v_max_f32_e32 v118, v119, v118
	v_max3_f32 v118, v118, v68, v69
	v_max3_f32 v118, v118, v70, v71
	v_max3_f32 v118, v118, v72, v73
	v_max3_f32 v118, v118, v74, v75
	v_max3_f32 v118, v118, v76, v77
	v_max3_f32 v118, v118, v78, v79
	v_max3_f32 v122, v118, v80, v81
	ds_read_b128 v[118:121], v183 offset:18432
	ds_read_b128 v[218:221], v183 offset:22528
	s_waitcnt lgkmcnt(1)
	v_mfma_f32_32x32x16_bf16 v[82:97], v[118:121], v[134:137], v[82:97]
	v_max3_f32 v118, v122, v98, v99
	v_max3_f32 v118, v118, v100, v101
	v_max3_f32 v118, v118, v102, v103
	v_max3_f32 v118, v118, v104, v105
	v_max3_f32 v118, v118, v106, v107
	v_max3_f32 v118, v118, v108, v109
	v_max3_f32 v118, v118, v110, v111
	v_max3_f32 v122, v118, v112, v113
	v_mov_b32_e32 v118, v122
	s_nop 1
	v_permlane32_swap_b32_e32 v122, v118
	ds_read_b128 v[222:225], v212 offset:22528
	ds_read_b128 v[226:229], v213 offset:22528
	v_max_f32_e32 v123, v118, v118
	ds_read_b128 v[118:121], v212 offset:18432
	s_waitcnt lgkmcnt(0)
	v_mfma_f32_32x32x16_bf16 v[82:97], v[118:121], v[138:141], v[82:97]
	v_max_f32_e32 v118, v122, v122
	v_max_f32_e32 v118, v118, v123
	v_sub_f32_e32 v120, v118, v188
	v_cmp_ge_f32_e32 vcc, s70, v120
	v_max_f32_e32 v119, v188, v188
	s_cmp_eq_u64 vcc, exec
	v_max_f32_e32 v118, v119, v118
	s_cselect_b64 vcc, -1, 0
	v_cndmask_b32_e32 v216, v118, v188, vcc
	v_sub_f32_e32 v118, v188, v216
	v_mul_f32_e32 v188, 0xbe38aa3b, v216
	v_mul_f32_e32 v189, 0x3e38aa3b, v118
	ds_read_b128 v[118:121], v213 offset:18432
	s_waitcnt lgkmcnt(0)
	v_mfma_f32_32x32x16_bf16 v[82:97], v[118:121], v[142:145], v[82:97]
	v_fma_f32 v66, v66, s18, v188
	v_fma_f32 v67, v67, s18, v188
	v_fma_f32 v68, v68, s18, v188
	v_fma_f32 v69, v69, s18, v188
	v_exp_f32_e32 v66, v66
	v_exp_f32_e32 v67, v67
	v_pk_fma_f32 v[70:71], v[70:71], s[18:19], v[188:189] op_sel_hi:[1,0,0]
	v_exp_f32_e32 v68, v68
	v_exp_f32_e32 v69, v69
	v_pk_fma_f32 v[72:73], v[72:73], s[18:19], v[188:189] op_sel_hi:[1,0,0]
	v_exp_f32_e32 v70, v70
	v_exp_f32_e32 v71, v71
	v_pk_fma_f32 v[74:75], v[74:75], s[18:19], v[188:189] op_sel_hi:[1,0,0]
	v_exp_f32_e32 v72, v72
	v_exp_f32_e32 v73, v73
	v_exp_f32_e32 v74, v74
	v_exp_f32_e32 v75, v75
	v_pk_add_f32 v[118:119], v[66:67], 0 op_sel_hi:[1,0]
	v_exp_f32_e32 v217, v189
	v_pk_add_f32 v[118:119], v[68:69], v[118:119]
	s_nop 0
	v_pk_add_f32 v[118:119], v[70:71], v[118:119]
	s_nop 0
	v_pk_add_f32 v[118:119], v[72:73], v[118:119]
	s_nop 0
	v_pk_add_f32 v[230:231], v[74:75], v[118:119]
	v_mfma_f32_32x32x16_bf16 v[114:129], v[114:117], v[130:133], 0
	v_mfma_f32_32x32x16_bf16 v[114:129], v[218:221], v[134:137], v[114:129]
	v_mfma_f32_32x32x16_bf16 v[114:129], v[222:225], v[138:141], v[114:129]
	v_mfma_f32_32x32x16_bf16 v[114:129], v[226:229], v[142:145], v[114:129]
	v_fma_f32 v76, v76, s18, v188
	v_fma_f32 v77, v77, s18, v188
	v_fma_f32 v78, v78, s18, v188
	v_fma_f32 v79, v79, s18, v188
	v_exp_f32_e32 v76, v76
	v_exp_f32_e32 v77, v77
	v_pk_fma_f32 v[80:81], v[80:81], s[18:19], v[188:189] op_sel_hi:[1,0,0]
	v_exp_f32_e32 v78, v78
	v_exp_f32_e32 v79, v79
	v_exp_f32_e32 v80, v80
	v_exp_f32_e32 v81, v81
	v_pk_fma_f32 v[98:99], v[98:99], s[18:19], v[188:189] op_sel_hi:[1,0,0]
	v_pk_fma_f32 v[100:101], v[100:101], s[18:19], v[188:189] op_sel_hi:[1,0,0]
	v_exp_f32_e32 v98, v98
	v_exp_f32_e32 v99, v99
	v_pk_add_f32 v[230:231], v[76:77], v[230:231]
	v_exp_f32_e32 v100, v100
	v_exp_f32_e32 v101, v101
	v_pk_add_f32 v[230:231], v[78:79], v[230:231]
	s_nop 0
	v_pk_add_f32 v[230:231], v[80:81], v[230:231]
	s_nop 0
	v_pk_add_f32 v[230:231], v[98:99], v[230:231]
	s_nop 0
	v_pk_add_f32 v[230:231], v[100:101], v[230:231]
	v_pk_fma_f32 v[102:103], v[102:103], s[18:19], v[188:189] op_sel_hi:[1,0,0]
	v_pk_fma_f32 v[104:105], v[104:105], s[18:19], v[188:189] op_sel_hi:[1,0,0]
	v_exp_f32_e32 v102, v102
	v_exp_f32_e32 v103, v103
	v_exp_f32_e32 v104, v104
	v_exp_f32_e32 v105, v105
	v_pk_fma_f32 v[106:107], v[106:107], s[18:19], v[188:189] op_sel_hi:[1,0,0]
	v_pk_fma_f32 v[108:109], v[108:109], s[18:19], v[188:189] op_sel_hi:[1,0,0]
	v_exp_f32_e32 v106, v106
	v_exp_f32_e32 v107, v107
	v_exp_f32_e32 v108, v108
	v_exp_f32_e32 v109, v109
	v_pk_fma_f32 v[110:111], v[110:111], s[18:19], v[188:189] op_sel_hi:[1,0,0]
	v_pk_add_f32 v[218:219], v[102:103], v[230:231]
	v_exp_f32_e32 v110, v110
	v_exp_f32_e32 v111, v111
	v_pk_add_f32 v[218:219], v[104:105], v[218:219]
	s_nop 0
	v_pk_add_f32 v[218:219], v[106:107], v[218:219]
	s_nop 0
	v_pk_add_f32 v[218:219], v[108:109], v[218:219]
	s_nop 0
	v_pk_add_f32 v[218:219], v[110:111], v[218:219]
	v_pk_fma_f32 v[112:113], v[112:113], s[18:19], v[188:189] op_sel_hi:[1,0,0]
	s_nop 0
	v_exp_f32_e32 v112, v112
	v_exp_f32_e32 v113, v113
	s_nop 0
	v_pk_add_f32 v[188:189], v[112:113], v[218:219]
	s_nop 0
	v_pk_add_f32 v[188:189], v[188:189], v[188:189] op_sel:[0,1] op_sel_hi:[1,0]
	s_nop 0
	v_mov_b32_e32 v189, v188
	s_nop 1
	v_permlane32_swap_b32_e32 v188, v189
	s_cbranch_vccnz .LBB0_1323
	s_waitcnt lgkmcnt(0)
	s_and_saveexec_b64 s[56:57], s[2:3]
	ds_write_b32 v204, v217
	s_or_b64 exec, exec, s[56:57]
	s_waitcnt lgkmcnt(0)
	v_add_u32_e32 v230, v203, v191
	ds_read_b128 v[218:221], v230 offset:96
	ds_read_b128 v[222:225], v230 offset:64
	ds_read_b128 v[226:229], v230 offset:32
	ds_read_b128 v[230:233], v230
	s_waitcnt lgkmcnt(0)
	s_waitcnt lgkmcnt(3)
	v_pk_mul_f32 v[62:63], v[62:63], v[218:219]
	s_waitcnt lgkmcnt(2)
	v_pk_mul_f32 v[58:59], v[58:59], v[222:223]
	s_waitcnt lgkmcnt(1)
	v_pk_mul_f32 v[54:55], v[54:55], v[226:227]
	v_pk_mul_f32 v[64:65], v[64:65], v[220:221]
	v_pk_mul_f32 v[60:61], v[60:61], v[224:225]
	v_pk_mul_f32 v[56:57], v[56:57], v[228:229]
	s_waitcnt lgkmcnt(0)
	v_pk_mul_f32 v[52:53], v[52:53], v[232:233]
	v_pk_mul_f32 v[50:51], v[50:51], v[230:231]
	v_pk_mul_f32 v[46:47], v[46:47], v[218:219]
	v_pk_mul_f32 v[42:43], v[42:43], v[222:223]
	v_pk_mul_f32 v[38:39], v[38:39], v[226:227]
	v_pk_mul_f32 v[48:49], v[48:49], v[220:221]
	v_pk_mul_f32 v[44:45], v[44:45], v[224:225]
	v_pk_mul_f32 v[40:41], v[40:41], v[228:229]
	v_pk_mul_f32 v[36:37], v[36:37], v[232:233]
	v_pk_mul_f32 v[34:35], v[34:35], v[230:231]
	v_pk_mul_f32 v[30:31], v[30:31], v[218:219]
	v_pk_mul_f32 v[26:27], v[26:27], v[222:223]
	v_pk_mul_f32 v[22:23], v[22:23], v[226:227]
	v_pk_mul_f32 v[32:33], v[32:33], v[220:221]
	v_pk_mul_f32 v[28:29], v[28:29], v[224:225]
	v_pk_mul_f32 v[24:25], v[24:25], v[228:229]
	v_pk_mul_f32 v[20:21], v[20:21], v[232:233]
	v_pk_mul_f32 v[18:19], v[18:19], v[230:231]
	v_pk_mul_f32 v[14:15], v[14:15], v[218:219]
	v_pk_mul_f32 v[10:11], v[10:11], v[222:223]
	v_pk_mul_f32 v[6:7], v[6:7], v[226:227]
	v_pk_mul_f32 v[16:17], v[16:17], v[220:221]
	v_pk_mul_f32 v[12:13], v[12:13], v[224:225]
	v_pk_mul_f32 v[8:9], v[8:9], v[228:229]
	v_pk_mul_f32 v[4:5], v[4:5], v[232:233]
	v_pk_mul_f32 v[2:3], v[2:3], v[230:231]

; DEVI void attn_item(const Params& p, const int l, const int bh, const int qblk, const float lam, const float osc, char* smem) {
;     ...
;   for (int kt = 0; kt < nkt; kt += 2) {
;     ATT_ITER(kt, pA0, pA1, pB0, pB1);
;     ATT_ITER(kt + 1, pB0, pB1, pA0, pA1);
.LBB0_1326:
	s_add_i32 s56, s52, 3
	s_cmp_lt_u32 s56, s53
	s_cselect_b64 s[54:55], -1, 0
	s_cmp_ge_u32 s56, s53
	s_waitcnt vmcnt(0)
	s_waitcnt lgkmcnt(0)
	s_barrier
	ds_read_b128 v[66:69], v181 offset:2048
	ds_read_b128 v[98:101], v181 offset:6144
	s_cbranch_scc0 .LBB0_1331
	s_and_b64 vcc, exec, s[8:9]
	s_cbranch_vccz .LBB0_1332

.LBB0_1331:
	s_add_u32 m0, s101, 0x4810
	s_nop 0
	global_load_lds_dwordx4 v242, s[40:41]
	s_add_u32 m0, s101, 0x6790
	s_nop 0
	global_load_lds_dwordx4 v242, s[40:41] offset:128
	s_and_b64 vcc, exec, s[8:9]
	s_cbranch_vccnz .LBB0_1328
.LBB0_1332:
	s_add_u32 m0, s101, 0x8810
	s_nop 0
	global_load_lds_dwordx4 v245, s[40:41]
	s_add_u32 m0, s101, 0xa810
	s_nop 0
	global_load_lds_dwordx4 v246, s[40:41]
	v_cmp_lt_u32_e32 vcc, s52, v214
	s_and_saveexec_b64 s[56:57], vcc
	s_cbranch_execz .LBB0_1329
.LBB0_1333:
	s_waitcnt lgkmcnt(1)
	v_mfma_f32_32x32x16_bf16 v[66:81], v[66:69], v[130:133], 0
	v_max_f32_e32 v102, v83, v83
	v_max_f32_e32 v103, v82, v82
	v_max_f32_e32 v102, v103, v102
	v_max3_f32 v102, v102, v84, v85
	v_max3_f32 v102, v102, v86, v87
	v_max3_f32 v102, v102, v88, v89
	v_max3_f32 v102, v102, v90, v91
	v_max3_f32 v102, v102, v92, v93
	v_max3_f32 v102, v102, v94, v95
	v_max3_f32 v106, v102, v96, v97
	ds_read_b128 v[102:105], v183 offset:2048
	ds_read_b128 v[216:219], v183 offset:6144
	s_waitcnt lgkmcnt(1)
	v_mfma_f32_32x32x16_bf16 v[66:81], v[102:105], v[134:137], v[66:81]
	v_max3_f32 v102, v106, v114, v115
	v_max3_f32 v102, v102, v116, v117
	v_max3_f32 v102, v102, v118, v119
	v_max3_f32 v102, v102, v120, v121
	v_max3_f32 v102, v102, v122, v123
	v_max3_f32 v102, v102, v124, v125
	v_max3_f32 v102, v102, v126, v127
	v_max3_f32 v106, v102, v128, v129
	v_mov_b32_e32 v102, v106
	s_nop 1
	v_permlane32_swap_b32_e32 v106, v102
	ds_read_b128 v[220:223], v212 offset:6144
	ds_read_b128 v[224:227], v213 offset:6144
	v_max_f32_e32 v107, v102, v102
	ds_read_b128 v[102:105], v212 offset:2048
	s_waitcnt lgkmcnt(0)
	v_mfma_f32_32x32x16_bf16 v[66:81], v[102:105], v[138:141], v[66:81]
	v_max_f32_e32 v102, v106, v106
	v_max_f32_e32 v102, v102, v107
	v_sub_f32_e32 v104, v102, v188
	v_cmp_ge_f32_e32 vcc, s70, v104
	v_max_f32_e32 v103, v188, v188
	s_cmp_eq_u64 vcc, exec
	v_max_f32_e32 v102, v103, v102
	s_cselect_b64 vcc, -1, 0
	v_cndmask_b32_e32 v186, v102, v188, vcc
	v_sub_f32_e32 v102, v188, v186
	v_mul_f32_e32 v184, 0xbe38aa3b, v186
	v_mul_f32_e32 v185, 0x3e38aa3b, v102
	ds_read_b128 v[102:105], v213 offset:2048
	s_waitcnt lgkmcnt(0)
	v_mfma_f32_32x32x16_bf16 v[66:81], v[102:105], v[142:145], v[66:81]
	v_fma_f32 v82, v82, s18, v184
	v_fma_f32 v83, v83, s18, v184
	v_fma_f32 v84, v84, s18, v184
	v_fma_f32 v85, v85, s18, v184
	v_exp_f32_e32 v82, v82
	v_exp_f32_e32 v83, v83
	v_pk_fma_f32 v[86:87], v[86:87], s[18:19], v[184:185] op_sel_hi:[1,0,0]
	v_exp_f32_e32 v84, v84
	v_exp_f32_e32 v85, v85
	v_pk_fma_f32 v[88:89], v[88:89], s[18:19], v[184:185] op_sel_hi:[1,0,0]
	v_exp_f32_e32 v86, v86
	v_exp_f32_e32 v87, v87
	v_pk_fma_f32 v[90:91], v[90:91], s[18:19], v[184:185] op_sel_hi:[1,0,0]
	v_exp_f32_e32 v88, v88
	v_exp_f32_e32 v89, v89
	v_exp_f32_e32 v90, v90
	v_exp_f32_e32 v91, v91
	v_pk_add_f32 v[102:103], v[82:83], 0 op_sel_hi:[1,0]
	v_exp_f32_e32 v187, v185
	v_pk_add_f32 v[102:103], v[84:85], v[102:103]
	s_nop 0
	v_pk_add_f32 v[102:103], v[86:87], v[102:103]
	s_nop 0
	v_pk_add_f32 v[102:103], v[88:89], v[102:103]
	s_nop 0
	v_pk_add_f32 v[188:189], v[90:91], v[102:103]
	v_mfma_f32_32x32x16_bf16 v[98:113], v[98:101], v[130:133], 0
	v_mfma_f32_32x32x16_bf16 v[98:113], v[216:219], v[134:137], v[98:113]
	v_mfma_f32_32x32x16_bf16 v[98:113], v[220:223], v[138:141], v[98:113]
	v_mfma_f32_32x32x16_bf16 v[98:113], v[224:227], v[142:145], v[98:113]
	v_fma_f32 v92, v92, s18, v184
	v_fma_f32 v93, v93, s18, v184
	v_fma_f32 v94, v94, s18, v184
	v_fma_f32 v95, v95, s18, v184
	v_exp_f32_e32 v92, v92
	v_exp_f32_e32 v93, v93
	v_pk_fma_f32 v[96:97], v[96:97], s[18:19], v[184:185] op_sel_hi:[1,0,0]
	v_exp_f32_e32 v94, v94
	v_exp_f32_e32 v95, v95
	v_exp_f32_e32 v96, v96
	v_exp_f32_e32 v97, v97
	v_pk_fma_f32 v[114:115], v[114:115], s[18:19], v[184:185] op_sel_hi:[1,0,0]
	v_pk_fma_f32 v[116:117], v[116:117], s[18:19], v[184:185] op_sel_hi:[1,0,0]
	v_exp_f32_e32 v114, v114
	v_exp_f32_e32 v115, v115
	v_pk_add_f32 v[188:189], v[92:93], v[188:189]
	v_exp_f32_e32 v116, v116
	v_exp_f32_e32 v117, v117
	v_pk_add_f32 v[188:189], v[94:95], v[188:189]
	s_nop 0
	v_pk_add_f32 v[188:189], v[96:97], v[188:189]
	s_nop 0
	v_pk_add_f32 v[188:189], v[114:115], v[188:189]
	s_nop 0
	v_pk_add_f32 v[188:189], v[116:117], v[188:189]
	v_pk_fma_f32 v[118:119], v[118:119], s[18:19], v[184:185] op_sel_hi:[1,0,0]
	v_pk_fma_f32 v[120:121], v[120:121], s[18:19], v[184:185] op_sel_hi:[1,0,0]
	v_exp_f32_e32 v118, v118
	v_exp_f32_e32 v119, v119
	v_exp_f32_e32 v120, v120
	v_exp_f32_e32 v121, v121
	v_pk_fma_f32 v[122:123], v[122:123], s[18:19], v[184:185] op_sel_hi:[1,0,0]
	v_pk_fma_f32 v[124:125], v[124:125], s[18:19], v[184:185] op_sel_hi:[1,0,0]
	v_exp_f32_e32 v122, v122
	v_exp_f32_e32 v123, v123
	v_exp_f32_e32 v124, v124
	v_exp_f32_e32 v125, v125
	v_pk_fma_f32 v[126:127], v[126:127], s[18:19], v[184:185] op_sel_hi:[1,0,0]
	v_pk_add_f32 v[188:189], v[118:119], v[188:189]
	v_exp_f32_e32 v126, v126
	v_exp_f32_e32 v127, v127
	v_pk_add_f32 v[188:189], v[120:121], v[188:189]
	s_nop 0
	v_pk_add_f32 v[188:189], v[122:123], v[188:189]
	s_nop 0
	v_pk_add_f32 v[188:189], v[124:125], v[188:189]
	s_nop 0
	v_pk_add_f32 v[188:189], v[126:127], v[188:189]
	v_pk_fma_f32 v[128:129], v[128:129], s[18:19], v[184:185] op_sel_hi:[1,0,0]
	s_nop 0
	v_exp_f32_e32 v128, v128
	v_exp_f32_e32 v129, v129
	s_nop 0
	v_pk_add_f32 v[184:185], v[128:129], v[188:189]
	s_nop 0
	v_pk_add_f32 v[184:185], v[184:185], v[184:185] op_sel:[0,1] op_sel_hi:[1,0]
	s_nop 0
	v_mov_b32_e32 v185, v184
	s_nop 1
	v_permlane32_swap_b32_e32 v184, v185
	s_cbranch_vccnz .LBB0_1337
	s_waitcnt lgkmcnt(0)
	s_and_saveexec_b64 s[58:59], s[2:3]
	ds_write_b32 v204, v187
	s_or_b64 exec, exec, s[58:59]
	s_waitcnt lgkmcnt(0)
	v_add_u32_e32 v188, v203, v191
	ds_read_b128 v[216:219], v188 offset:96
	ds_read_b128 v[220:223], v188 offset:64
	ds_read_b128 v[224:227], v188 offset:32
	ds_read_b128 v[228:231], v188
	s_waitcnt lgkmcnt(0)
	s_waitcnt lgkmcnt(3)
	v_pk_mul_f32 v[62:63], v[62:63], v[216:217]
	s_waitcnt lgkmcnt(2)
	v_pk_mul_f32 v[58:59], v[58:59], v[220:221]
	s_waitcnt lgkmcnt(1)
	v_pk_mul_f32 v[54:55], v[54:55], v[224:225]
	v_pk_mul_f32 v[64:65], v[64:65], v[218:219]
	v_pk_mul_f32 v[60:61], v[60:61], v[222:223]
	v_pk_mul_f32 v[56:57], v[56:57], v[226:227]
	s_waitcnt lgkmcnt(0)
	v_pk_mul_f32 v[52:53], v[52:53], v[230:231]
	v_pk_mul_f32 v[50:51], v[50:51], v[228:229]
	v_pk_mul_f32 v[46:47], v[46:47], v[216:217]
	v_pk_mul_f32 v[42:43], v[42:43], v[220:221]
	v_pk_mul_f32 v[38:39], v[38:39], v[224:225]
	v_pk_mul_f32 v[48:49], v[48:49], v[218:219]
	v_pk_mul_f32 v[44:45], v[44:45], v[222:223]
	v_pk_mul_f32 v[40:41], v[40:41], v[226:227]
	v_pk_mul_f32 v[36:37], v[36:37], v[230:231]
	v_pk_mul_f32 v[34:35], v[34:35], v[228:229]
	v_pk_mul_f32 v[30:31], v[30:31], v[216:217]
	v_pk_mul_f32 v[26:27], v[26:27], v[220:221]
	v_pk_mul_f32 v[22:23], v[22:23], v[224:225]
	v_pk_mul_f32 v[32:33], v[32:33], v[218:219]
	v_pk_mul_f32 v[28:29], v[28:29], v[222:223]
	v_pk_mul_f32 v[24:25], v[24:25], v[226:227]
	v_pk_mul_f32 v[20:21], v[20:21], v[230:231]
	v_pk_mul_f32 v[18:19], v[18:19], v[228:229]
	v_pk_mul_f32 v[14:15], v[14:15], v[216:217]
	v_pk_mul_f32 v[10:11], v[10:11], v[220:221]
	v_pk_mul_f32 v[6:7], v[6:7], v[224:225]
	v_pk_mul_f32 v[16:17], v[16:17], v[218:219]
	v_pk_mul_f32 v[12:13], v[12:13], v[222:223]
	v_pk_mul_f32 v[8:9], v[8:9], v[226:227]
	v_pk_mul_f32 v[4:5], v[4:5], v[230:231]
	v_pk_mul_f32 v[2:3], v[2:3], v[228:229]
